# noS6 + P14/P15 hoist + early P11 conversions + static prio (waves 4-7) + saddr DMA at all K-loop sites (scratch s100:101), conv0 dropped
# speedup vs baseline: 1.0095x; 1.0058x over previous
.Lmy_prio_skip0:
.LBB0_116:
	ds_read_b128 v[128:131], v229
	ds_read_b128 v[132:135], v229 offset:1024
	ds_read_b128 v[136:139], v229 offset:2048
	ds_read_b128 v[140:143], v229 offset:3072
	ds_read_b128 v[144:147], v230
	ds_read_b128 v[148:151], v230 offset:1024
	ds_read_b128 v[152:155], v230 offset:2048
	ds_read_b128 v[156:159], v230 offset:3072
	s_add_u32 vcc_lo, s94, 0x100
	s_addc_u32 vcc_hi, s95, 0
	s_cmp_eq_u32 s37, 60
	s_cselect_b32 s53, s89, vcc_hi
	s_cselect_b32 s52, s93, vcc_lo
	s_cselect_b32 s97, s85, s36
	s_cselect_b32 s96, s34, s35
	s_add_i32 m0, s67, 0xc000
	ds_read_b128 v[160:163], v231
	ds_read_b128 v[164:167], v231 offset:1024
	ds_read_b128 v[186:189], v231 offset:2048
	ds_read_b128 v[190:193], v231 offset:3072
	ds_read_b128 v[194:197], v231 offset:4096
	ds_read_b128 v[198:201], v231 offset:5120
	ds_read_b128 v[202:205], v231 offset:6144
	ds_read_b128 v[206:209], v231 offset:7168
	global_load_lds_dwordx4 v178, s[94:95]
	s_add_i32 m0, s67, 0xe000
	s_nop 0
	global_load_lds_dwordx4 v180, s[94:95]
	s_waitcnt vmcnt(8)
	s_waitcnt lgkmcnt(0)
	s_barrier
	s_waitcnt lgkmcnt(0)
	v_mfma_f32_16x16x32_bf16 v[124:127], v[128:131], v[160:163], v[124:127]
	v_mfma_f32_16x16x32_bf16 v[120:123], v[136:139], v[160:163], v[120:123]
	v_mfma_f32_16x16x32_bf16 v[112:115], v[128:131], v[186:189], v[112:115]
	v_mfma_f32_16x16x32_bf16 v[104:107], v[136:139], v[186:189], v[104:107]
	v_mfma_f32_16x16x32_bf16 v[96:99], v[128:131], v[194:197], v[96:99]
	v_mfma_f32_16x16x32_bf16 v[88:91], v[136:139], v[194:197], v[88:91]
	v_mfma_f32_16x16x32_bf16 v[80:83], v[128:131], v[202:205], v[80:83]
	v_mfma_f32_16x16x32_bf16 v[72:75], v[136:139], v[202:205], v[72:75]
	v_mfma_f32_16x16x32_bf16 v[124:127], v[132:135], v[164:167], v[124:127]
	v_mfma_f32_16x16x32_bf16 v[120:123], v[140:143], v[164:167], v[120:123]
	v_mfma_f32_16x16x32_bf16 v[112:115], v[132:135], v[190:193], v[112:115]
	v_mfma_f32_16x16x32_bf16 v[104:107], v[140:143], v[190:193], v[104:107]
	v_mfma_f32_16x16x32_bf16 v[96:99], v[132:135], v[198:201], v[96:99]
	v_mfma_f32_16x16x32_bf16 v[88:91], v[140:143], v[198:201], v[88:91]
	v_mfma_f32_16x16x32_bf16 v[80:83], v[132:135], v[206:209], v[80:83]
	v_mfma_f32_16x16x32_bf16 v[72:75], v[140:143], v[206:209], v[72:75]
	v_mfma_f32_16x16x32_bf16 v[116:119], v[144:147], v[160:163], v[116:119]
	v_mfma_f32_16x16x32_bf16 v[108:111], v[152:155], v[160:163], v[108:111]
	v_mfma_f32_16x16x32_bf16 v[100:103], v[144:147], v[186:189], v[100:103]
	v_mfma_f32_16x16x32_bf16 v[92:95], v[152:155], v[186:189], v[92:95]
	v_mfma_f32_16x16x32_bf16 v[84:87], v[144:147], v[194:197], v[84:87]
	v_mfma_f32_16x16x32_bf16 v[76:79], v[152:155], v[194:197], v[76:79]
	v_mfma_f32_16x16x32_bf16 v[68:71], v[144:147], v[202:205], v[68:71]
	v_mfma_f32_16x16x32_bf16 v[64:67], v[152:155], v[202:205], v[64:67]
	v_mfma_f32_16x16x32_bf16 v[116:119], v[148:151], v[164:167], v[116:119]
	v_mfma_f32_16x16x32_bf16 v[108:111], v[156:159], v[164:167], v[108:111]
	v_mfma_f32_16x16x32_bf16 v[100:103], v[148:151], v[190:193], v[100:103]
	v_mfma_f32_16x16x32_bf16 v[92:95], v[156:159], v[190:193], v[92:95]
	v_mfma_f32_16x16x32_bf16 v[84:87], v[148:151], v[198:201], v[84:87]
	v_mfma_f32_16x16x32_bf16 v[76:79], v[156:159], v[198:201], v[76:79]
	v_mfma_f32_16x16x32_bf16 v[68:71], v[148:151], v[206:209], v[68:71]
	v_mfma_f32_16x16x32_bf16 v[64:67], v[156:159], v[206:209], v[64:67]
	s_barrier
	s_add_i32 s38, s81, s91
	s_mov_b32 m0, s38
	ds_read_b128 v[160:163], v231 offset:16384
	ds_read_b128 v[164:167], v231 offset:17408
	ds_read_b128 v[186:189], v231 offset:18432
	ds_read_b128 v[190:193], v231 offset:19456
	ds_read_b128 v[194:197], v231 offset:20480
	ds_read_b128 v[198:201], v231 offset:21504
	ds_read_b128 v[202:205], v231 offset:22528
	ds_read_b128 v[206:209], v231 offset:23552
	global_load_lds_dwordx4 v170, s[96:97]
	s_add_i32 m0, s38, 0x2000
	s_add_u32 s38, s96, 0x100000
	s_addc_u32 s39, s97, 0
	s_add_i32 s40, s14, s91
	global_load_lds_dwordx4 v174, s[96:97]
	s_mov_b32 m0, s40
	global_load_lds_dwordx4 v170, s[38:39]
	s_add_i32 m0, s40, 0x2000
	s_nop 0
	global_load_lds_dwordx4 v174, s[38:39]
	s_mov_b32 m0, s67
	s_nop 0
	global_load_lds_dwordx4 v168, s[52:53]
	s_mov_b32 m0, s16
	s_nop 0
	global_load_lds_dwordx4 v172, s[52:53]
	s_waitcnt vmcnt(8)
	s_waitcnt lgkmcnt(0)
	s_barrier
	s_waitcnt lgkmcnt(0)
	v_mfma_f32_16x16x32_bf16 v[60:63], v[128:131], v[160:163], v[60:63]
	v_mfma_f32_16x16x32_bf16 v[56:59], v[136:139], v[160:163], v[56:59]
	v_mfma_f32_16x16x32_bf16 v[44:47], v[128:131], v[186:189], v[44:47]
	v_mfma_f32_16x16x32_bf16 v[40:43], v[136:139], v[186:189], v[40:43]
	v_mfma_f32_16x16x32_bf16 v[28:31], v[128:131], v[194:197], v[28:31]
	v_mfma_f32_16x16x32_bf16 v[24:27], v[136:139], v[194:197], v[24:27]
	v_mfma_f32_16x16x32_bf16 v[12:15], v[128:131], v[202:205], v[12:15]
	v_mfma_f32_16x16x32_bf16 v[8:11], v[136:139], v[202:205], v[8:11]
	v_mfma_f32_16x16x32_bf16 v[60:63], v[132:135], v[164:167], v[60:63]
	v_mfma_f32_16x16x32_bf16 v[56:59], v[140:143], v[164:167], v[56:59]
	v_mfma_f32_16x16x32_bf16 v[44:47], v[132:135], v[190:193], v[44:47]
	v_mfma_f32_16x16x32_bf16 v[40:43], v[140:143], v[190:193], v[40:43]
	v_mfma_f32_16x16x32_bf16 v[28:31], v[132:135], v[198:201], v[28:31]
	v_mfma_f32_16x16x32_bf16 v[24:27], v[140:143], v[198:201], v[24:27]
	v_mfma_f32_16x16x32_bf16 v[12:15], v[132:135], v[206:209], v[12:15]
	v_mfma_f32_16x16x32_bf16 v[8:11], v[140:143], v[206:209], v[8:11]
	v_mfma_f32_16x16x32_bf16 v[52:55], v[144:147], v[160:163], v[52:55]
	v_mfma_f32_16x16x32_bf16 v[48:51], v[152:155], v[160:163], v[48:51]
	v_mfma_f32_16x16x32_bf16 v[36:39], v[144:147], v[186:189], v[36:39]
	v_mfma_f32_16x16x32_bf16 v[32:35], v[152:155], v[186:189], v[32:35]
	v_mfma_f32_16x16x32_bf16 v[20:23], v[144:147], v[194:197], v[20:23]
	v_mfma_f32_16x16x32_bf16 v[16:19], v[152:155], v[194:197], v[16:19]
	v_mfma_f32_16x16x32_bf16 v[4:7], v[144:147], v[202:205], v[4:7]
	v_mfma_f32_16x16x32_bf16 v[0:3], v[152:155], v[202:205], v[0:3]
	v_mfma_f32_16x16x32_bf16 v[52:55], v[148:151], v[164:167], v[52:55]
	v_mfma_f32_16x16x32_bf16 v[48:51], v[156:159], v[164:167], v[48:51]
	v_mfma_f32_16x16x32_bf16 v[36:39], v[148:151], v[190:193], v[36:39]
	v_mfma_f32_16x16x32_bf16 v[32:35], v[156:159], v[190:193], v[32:35]
	v_mfma_f32_16x16x32_bf16 v[20:23], v[148:151], v[198:201], v[20:23]
	v_mfma_f32_16x16x32_bf16 v[16:19], v[156:159], v[198:201], v[16:19]
	v_mfma_f32_16x16x32_bf16 v[4:7], v[148:151], v[206:209], v[4:7]
	v_mfma_f32_16x16x32_bf16 v[0:3], v[156:159], v[206:209], v[0:3]
	s_barrier
	s_add_i32 s40, 0, 0x18000
	s_add_i32 s41, 0, 0x1c000
	v_add_u32_e32 v140, s40, v225
	v_add_u32_e32 v156, s41, v225
	ds_read_b128 v[128:131], v140
	ds_read_b128 v[132:135], v140 offset:1024
	ds_read_b128 v[136:139], v140 offset:2048
	ds_read_b128 v[140:143], v140 offset:3072
	ds_read_b128 v[144:147], v156
	ds_read_b128 v[148:151], v156 offset:1024
	ds_read_b128 v[152:155], v156 offset:2048
	ds_read_b128 v[156:159], v156 offset:3072
	s_add_u32 s38, s52, 0x100000
	s_addc_u32 s39, s53, 0
	s_mov_b32 m0, s17
	ds_read_b128 v[160:163], v231 offset:32768
	ds_read_b128 v[164:167], v231 offset:33792
	ds_read_b128 v[186:189], v231 offset:34816
	ds_read_b128 v[190:193], v231 offset:35840
	ds_read_b128 v[194:197], v231 offset:36864
	ds_read_b128 v[198:201], v231 offset:37888
	ds_read_b128 v[202:205], v231 offset:38912
	ds_read_b128 v[206:209], v231 offset:39936
	global_load_lds_dwordx4 v168, s[38:39]
	s_mov_b32 m0, s10
	s_nop 0
	global_load_lds_dwordx4 v172, s[38:39]
	s_waitcnt vmcnt(8)
	s_waitcnt lgkmcnt(0)
	s_barrier
	s_waitcnt lgkmcnt(0)
	v_mfma_f32_16x16x32_bf16 v[124:127], v[128:131], v[160:163], v[124:127]
	v_mfma_f32_16x16x32_bf16 v[120:123], v[136:139], v[160:163], v[120:123]
	v_mfma_f32_16x16x32_bf16 v[112:115], v[128:131], v[186:189], v[112:115]
	v_mfma_f32_16x16x32_bf16 v[104:107], v[136:139], v[186:189], v[104:107]
	v_mfma_f32_16x16x32_bf16 v[96:99], v[128:131], v[194:197], v[96:99]
	v_mfma_f32_16x16x32_bf16 v[88:91], v[136:139], v[194:197], v[88:91]
	v_mfma_f32_16x16x32_bf16 v[80:83], v[128:131], v[202:205], v[80:83]
	v_mfma_f32_16x16x32_bf16 v[72:75], v[136:139], v[202:205], v[72:75]
	v_mfma_f32_16x16x32_bf16 v[124:127], v[132:135], v[164:167], v[124:127]
	v_mfma_f32_16x16x32_bf16 v[120:123], v[140:143], v[164:167], v[120:123]
	v_mfma_f32_16x16x32_bf16 v[112:115], v[132:135], v[190:193], v[112:115]
	v_mfma_f32_16x16x32_bf16 v[104:107], v[140:143], v[190:193], v[104:107]
	v_mfma_f32_16x16x32_bf16 v[96:99], v[132:135], v[198:201], v[96:99]
	v_mfma_f32_16x16x32_bf16 v[88:91], v[140:143], v[198:201], v[88:91]
	v_mfma_f32_16x16x32_bf16 v[80:83], v[132:135], v[206:209], v[80:83]
	v_mfma_f32_16x16x32_bf16 v[72:75], v[140:143], v[206:209], v[72:75]
	v_mfma_f32_16x16x32_bf16 v[116:119], v[144:147], v[160:163], v[116:119]
	v_mfma_f32_16x16x32_bf16 v[108:111], v[152:155], v[160:163], v[108:111]
	v_mfma_f32_16x16x32_bf16 v[100:103], v[144:147], v[186:189], v[100:103]
	v_mfma_f32_16x16x32_bf16 v[92:95], v[152:155], v[186:189], v[92:95]
	v_mfma_f32_16x16x32_bf16 v[84:87], v[144:147], v[194:197], v[84:87]
	v_mfma_f32_16x16x32_bf16 v[76:79], v[152:155], v[194:197], v[76:79]
	v_mfma_f32_16x16x32_bf16 v[68:71], v[144:147], v[202:205], v[68:71]
	v_mfma_f32_16x16x32_bf16 v[64:67], v[152:155], v[202:205], v[64:67]
	v_mfma_f32_16x16x32_bf16 v[116:119], v[148:151], v[164:167], v[116:119]
	v_mfma_f32_16x16x32_bf16 v[108:111], v[156:159], v[164:167], v[108:111]
	v_mfma_f32_16x16x32_bf16 v[100:103], v[148:151], v[190:193], v[100:103]
	v_mfma_f32_16x16x32_bf16 v[92:95], v[156:159], v[190:193], v[92:95]
	v_mfma_f32_16x16x32_bf16 v[84:87], v[148:151], v[198:201], v[84:87]
	v_mfma_f32_16x16x32_bf16 v[76:79], v[156:159], v[198:201], v[76:79]
	v_mfma_f32_16x16x32_bf16 v[68:71], v[148:151], v[206:209], v[68:71]
	v_mfma_f32_16x16x32_bf16 v[64:67], v[156:159], v[206:209], v[64:67]
	s_barrier
	s_add_i32 s38, s40, s91
	s_mov_b32 m0, s38
	ds_read_b128 v[160:163], v231 offset:49152
	ds_read_b128 v[164:167], v231 offset:50176
	ds_read_b128 v[186:189], v231 offset:51200
	ds_read_b128 v[190:193], v231 offset:52224
	ds_read_b128 v[194:197], v231 offset:53248
	ds_read_b128 v[198:201], v231 offset:54272
	ds_read_b128 v[202:205], v231 offset:55296
	ds_read_b128 v[206:209], v231 offset:56320
	s_add_u32 s100, s96, 0x80
	s_addc_u32 s101, s97, 0
	global_load_lds_dwordx4 v170, s[100:101]
	s_add_i32 m0, s38, 0x2000
	s_add_u32 s38, s96, 0x100080
	s_addc_u32 s39, s97, 0
	s_add_i32 s40, s41, s91
	s_add_u32 s100, s96, 0x80
	s_addc_u32 s101, s97, 0
	global_load_lds_dwordx4 v174, s[100:101]
	s_mov_b32 m0, s40
	s_nop 0
	global_load_lds_dwordx4 v170, s[38:39]
	s_add_i32 m0, s40, 0x2000
	s_nop 0
	global_load_lds_dwordx4 v174, s[38:39]
	s_mov_b32 m0, s13
	s_nop 0
	s_add_u32 s100, s52, 0x80
	s_addc_u32 s101, s53, 0
	global_load_lds_dwordx4 v168, s[100:101]
	s_mov_b32 m0, s77
	s_nop 0
	s_add_u32 s100, s52, 0x80
	s_addc_u32 s101, s53, 0
	global_load_lds_dwordx4 v172, s[100:101]
	s_waitcnt vmcnt(8)
	s_waitcnt lgkmcnt(0)
	s_barrier
	s_waitcnt lgkmcnt(0)
	v_mfma_f32_16x16x32_bf16 v[60:63], v[128:131], v[160:163], v[60:63]
	v_mfma_f32_16x16x32_bf16 v[56:59], v[136:139], v[160:163], v[56:59]
	v_mfma_f32_16x16x32_bf16 v[44:47], v[128:131], v[186:189], v[44:47]
	v_mfma_f32_16x16x32_bf16 v[40:43], v[136:139], v[186:189], v[40:43]
	v_mfma_f32_16x16x32_bf16 v[28:31], v[128:131], v[194:197], v[28:31]
	v_mfma_f32_16x16x32_bf16 v[24:27], v[136:139], v[194:197], v[24:27]
	v_mfma_f32_16x16x32_bf16 v[12:15], v[128:131], v[202:205], v[12:15]
	v_mfma_f32_16x16x32_bf16 v[8:11], v[136:139], v[202:205], v[8:11]
	v_mfma_f32_16x16x32_bf16 v[60:63], v[132:135], v[164:167], v[60:63]
	v_mfma_f32_16x16x32_bf16 v[56:59], v[140:143], v[164:167], v[56:59]
	v_mfma_f32_16x16x32_bf16 v[44:47], v[132:135], v[190:193], v[44:47]
	v_mfma_f32_16x16x32_bf16 v[40:43], v[140:143], v[190:193], v[40:43]
	v_mfma_f32_16x16x32_bf16 v[28:31], v[132:135], v[198:201], v[28:31]
	v_mfma_f32_16x16x32_bf16 v[24:27], v[140:143], v[198:201], v[24:27]
	v_mfma_f32_16x16x32_bf16 v[12:15], v[132:135], v[206:209], v[12:15]
	v_mfma_f32_16x16x32_bf16 v[8:11], v[140:143], v[206:209], v[8:11]
	v_mfma_f32_16x16x32_bf16 v[52:55], v[144:147], v[160:163], v[52:55]
	v_mfma_f32_16x16x32_bf16 v[48:51], v[152:155], v[160:163], v[48:51]
	v_mfma_f32_16x16x32_bf16 v[36:39], v[144:147], v[186:189], v[36:39]
	v_mfma_f32_16x16x32_bf16 v[32:35], v[152:155], v[186:189], v[32:35]
	v_mfma_f32_16x16x32_bf16 v[20:23], v[144:147], v[194:197], v[20:23]
	v_mfma_f32_16x16x32_bf16 v[16:19], v[152:155], v[194:197], v[16:19]
	v_mfma_f32_16x16x32_bf16 v[4:7], v[144:147], v[202:205], v[4:7]
	v_mfma_f32_16x16x32_bf16 v[0:3], v[152:155], v[202:205], v[0:3]
	v_mfma_f32_16x16x32_bf16 v[52:55], v[148:151], v[164:167], v[52:55]
	v_mfma_f32_16x16x32_bf16 v[48:51], v[156:159], v[164:167], v[48:51]
	v_mfma_f32_16x16x32_bf16 v[36:39], v[148:151], v[190:193], v[36:39]
	v_mfma_f32_16x16x32_bf16 v[32:35], v[156:159], v[190:193], v[32:35]
	v_mfma_f32_16x16x32_bf16 v[20:23], v[148:151], v[198:201], v[20:23]
	v_mfma_f32_16x16x32_bf16 v[16:19], v[156:159], v[198:201], v[16:19]
	v_mfma_f32_16x16x32_bf16 v[4:7], v[148:151], v[206:209], v[4:7]
	v_mfma_f32_16x16x32_bf16 v[0:3], v[156:159], v[206:209], v[0:3]
	s_barrier
	s_add_i32 s37, s37, 2
	s_add_u32 s35, s35, 0x100
	s_addc_u32 s36, s36, 0
	s_cmp_gt_u32 s37, 61
	s_mov_b64 s[94:95], vcc
	s_cbranch_scc0 .LBB0_116
	s_setprio 0
	s_and_b64 vcc, exec, s[64:65]
	s_cbranch_vccz .LBB0_119
	s_barrier

.Lmy_prio_skip1:
.LBB0_521:
	ds_read_b128 v[152:155], v149
	ds_read_b128 v[156:159], v149 offset:1024
	ds_read_b128 v[160:163], v149 offset:2048
	ds_read_b128 v[164:167], v149 offset:3072
	ds_read_b128 v[168:171], v150
	ds_read_b128 v[172:175], v150 offset:1024
	ds_read_b128 v[176:179], v150 offset:2048
	ds_read_b128 v[180:183], v150 offset:3072
	s_add_u32 s37, s46, 0xfff80080
	s_addc_u32 s38, s47, -1
	s_cmp_eq_u32 s36, 28
	s_cselect_b32 s51, s13, s38
	s_cselect_b32 s50, s64, s37
	s_cselect_b32 s49, s11, s35
	s_cselect_b32 s48, s65, s34
	s_add_i32 m0, s17, 0xc000
	ds_read_b128 v[184:187], v151
	ds_read_b128 v[188:191], v151 offset:1024
	ds_read_b128 v[192:195], v151 offset:2048
	ds_read_b128 v[196:199], v151 offset:3072
	ds_read_b128 v[200:203], v151 offset:4096
	ds_read_b128 v[204:207], v151 offset:5120
	ds_read_b128 v[208:211], v151 offset:6144
	ds_read_b128 v[212:215], v151 offset:7168
	global_load_lds_dwordx4 v136, s[46:47]
	s_add_i32 m0, s17, 0xe000
	s_nop 0
	global_load_lds_dwordx4 v138, s[46:47]
	s_waitcnt vmcnt(8)
	s_waitcnt lgkmcnt(0)
	s_barrier
	s_waitcnt lgkmcnt(0)
	v_mfma_f32_16x16x32_bf16 v[124:127], v[152:155], v[184:187], v[124:127]
	v_mfma_f32_16x16x32_bf16 v[120:123], v[160:163], v[184:187], v[120:123]
	v_mfma_f32_16x16x32_bf16 v[116:119], v[152:155], v[192:195], v[116:119]
	v_mfma_f32_16x16x32_bf16 v[108:111], v[160:163], v[192:195], v[108:111]
	v_mfma_f32_16x16x32_bf16 v[100:103], v[152:155], v[200:203], v[100:103]
	v_mfma_f32_16x16x32_bf16 v[92:95], v[160:163], v[200:203], v[92:95]
	v_mfma_f32_16x16x32_bf16 v[84:87], v[152:155], v[208:211], v[84:87]
	v_mfma_f32_16x16x32_bf16 v[76:79], v[160:163], v[208:211], v[76:79]
	v_mfma_f32_16x16x32_bf16 v[124:127], v[156:159], v[188:191], v[124:127]
	v_mfma_f32_16x16x32_bf16 v[120:123], v[164:167], v[188:191], v[120:123]
	v_mfma_f32_16x16x32_bf16 v[116:119], v[156:159], v[196:199], v[116:119]
	v_mfma_f32_16x16x32_bf16 v[108:111], v[164:167], v[196:199], v[108:111]
	v_mfma_f32_16x16x32_bf16 v[100:103], v[156:159], v[204:207], v[100:103]
	v_mfma_f32_16x16x32_bf16 v[92:95], v[164:167], v[204:207], v[92:95]
	v_mfma_f32_16x16x32_bf16 v[84:87], v[156:159], v[212:215], v[84:87]
	v_mfma_f32_16x16x32_bf16 v[76:79], v[164:167], v[212:215], v[76:79]
	v_mfma_f32_16x16x32_bf16 v[112:115], v[168:171], v[184:187], v[112:115]
	v_mfma_f32_16x16x32_bf16 v[104:107], v[176:179], v[184:187], v[104:107]
	v_mfma_f32_16x16x32_bf16 v[96:99], v[168:171], v[192:195], v[96:99]
	v_mfma_f32_16x16x32_bf16 v[88:91], v[176:179], v[192:195], v[88:91]
	v_mfma_f32_16x16x32_bf16 v[80:83], v[168:171], v[200:203], v[80:83]
	v_mfma_f32_16x16x32_bf16 v[72:75], v[176:179], v[200:203], v[72:75]
	v_mfma_f32_16x16x32_bf16 v[68:71], v[168:171], v[208:211], v[68:71]
	v_mfma_f32_16x16x32_bf16 v[64:67], v[176:179], v[208:211], v[64:67]
	v_mfma_f32_16x16x32_bf16 v[112:115], v[172:175], v[188:191], v[112:115]
	v_mfma_f32_16x16x32_bf16 v[104:107], v[180:183], v[188:191], v[104:107]
	v_mfma_f32_16x16x32_bf16 v[96:99], v[172:175], v[196:199], v[96:99]
	v_mfma_f32_16x16x32_bf16 v[88:91], v[180:183], v[196:199], v[88:91]
	v_mfma_f32_16x16x32_bf16 v[80:83], v[172:175], v[204:207], v[80:83]
	v_mfma_f32_16x16x32_bf16 v[72:75], v[180:183], v[204:207], v[72:75]
	v_mfma_f32_16x16x32_bf16 v[68:71], v[172:175], v[212:215], v[68:71]
	v_mfma_f32_16x16x32_bf16 v[64:67], v[180:183], v[212:215], v[64:67]
	s_barrier
	s_add_i32 s37, s61, s53
	s_mov_b32 m0, s37
	ds_read_b128 v[184:187], v151 offset:16384
	ds_read_b128 v[188:191], v151 offset:17408
	ds_read_b128 v[192:195], v151 offset:18432
	ds_read_b128 v[196:199], v151 offset:19456
	ds_read_b128 v[200:203], v151 offset:20480
	ds_read_b128 v[204:207], v151 offset:21504
	ds_read_b128 v[208:211], v151 offset:22528
	ds_read_b128 v[212:215], v151 offset:23552
	global_load_lds_dwordx4 v130, s[48:49]
	s_add_i32 m0, s37, 0x2000
	s_add_u32 s38, s48, 0x80000
	s_addc_u32 s39, s49, 0
	s_add_i32 s37, s62, s53
	global_load_lds_dwordx4 v134, s[48:49]
	s_mov_b32 m0, s37
	global_load_lds_dwordx4 v130, s[38:39]
	s_add_i32 m0, s37, 0x2000
	s_nop 0
	global_load_lds_dwordx4 v134, s[38:39]
	s_mov_b32 m0, s17
	s_nop 0
	global_load_lds_dwordx4 v128, s[50:51]
	s_mov_b32 m0, s54
	s_nop 0
	global_load_lds_dwordx4 v132, s[50:51]
	s_waitcnt vmcnt(8)
	s_waitcnt lgkmcnt(0)
	s_barrier
	s_waitcnt lgkmcnt(0)
	v_mfma_f32_16x16x32_bf16 v[60:63], v[152:155], v[184:187], v[60:63]
	v_mfma_f32_16x16x32_bf16 v[56:59], v[160:163], v[184:187], v[56:59]
	v_mfma_f32_16x16x32_bf16 v[52:55], v[152:155], v[192:195], v[52:55]
	v_mfma_f32_16x16x32_bf16 v[44:47], v[160:163], v[192:195], v[44:47]
	v_mfma_f32_16x16x32_bf16 v[36:39], v[152:155], v[200:203], v[36:39]
	v_mfma_f32_16x16x32_bf16 v[28:31], v[160:163], v[200:203], v[28:31]
	v_mfma_f32_16x16x32_bf16 v[20:23], v[152:155], v[208:211], v[20:23]
	v_mfma_f32_16x16x32_bf16 v[12:15], v[160:163], v[208:211], v[12:15]
	v_mfma_f32_16x16x32_bf16 v[60:63], v[156:159], v[188:191], v[60:63]
	v_mfma_f32_16x16x32_bf16 v[56:59], v[164:167], v[188:191], v[56:59]
	v_mfma_f32_16x16x32_bf16 v[52:55], v[156:159], v[196:199], v[52:55]
	v_mfma_f32_16x16x32_bf16 v[44:47], v[164:167], v[196:199], v[44:47]
	v_mfma_f32_16x16x32_bf16 v[36:39], v[156:159], v[204:207], v[36:39]
	v_mfma_f32_16x16x32_bf16 v[28:31], v[164:167], v[204:207], v[28:31]
	v_mfma_f32_16x16x32_bf16 v[20:23], v[156:159], v[212:215], v[20:23]
	v_mfma_f32_16x16x32_bf16 v[12:15], v[164:167], v[212:215], v[12:15]
	v_mfma_f32_16x16x32_bf16 v[48:51], v[168:171], v[184:187], v[48:51]
	v_mfma_f32_16x16x32_bf16 v[40:43], v[176:179], v[184:187], v[40:43]
	v_mfma_f32_16x16x32_bf16 v[32:35], v[168:171], v[192:195], v[32:35]
	v_mfma_f32_16x16x32_bf16 v[24:27], v[176:179], v[192:195], v[24:27]
	v_mfma_f32_16x16x32_bf16 v[16:19], v[168:171], v[200:203], v[16:19]
	v_mfma_f32_16x16x32_bf16 v[8:11], v[176:179], v[200:203], v[8:11]
	v_mfma_f32_16x16x32_bf16 v[4:7], v[168:171], v[208:211], v[4:7]
	v_mfma_f32_16x16x32_bf16 v[0:3], v[176:179], v[208:211], v[0:3]
	v_mfma_f32_16x16x32_bf16 v[48:51], v[172:175], v[188:191], v[48:51]
	v_mfma_f32_16x16x32_bf16 v[40:43], v[180:183], v[188:191], v[40:43]
	v_mfma_f32_16x16x32_bf16 v[32:35], v[172:175], v[196:199], v[32:35]
	v_mfma_f32_16x16x32_bf16 v[24:27], v[180:183], v[196:199], v[24:27]
	v_mfma_f32_16x16x32_bf16 v[16:19], v[172:175], v[204:207], v[16:19]
	v_mfma_f32_16x16x32_bf16 v[8:11], v[180:183], v[204:207], v[8:11]
	v_mfma_f32_16x16x32_bf16 v[4:7], v[172:175], v[212:215], v[4:7]
	v_mfma_f32_16x16x32_bf16 v[0:3], v[180:183], v[212:215], v[0:3]
	s_barrier
	s_add_i32 s37, 0, 0x18000
	s_add_i32 s40, 0, 0x1c000
	v_add_u32_e32 v164, s37, v147
	v_add_u32_e32 v180, s40, v147
	ds_read_b128 v[152:155], v164
	ds_read_b128 v[156:159], v164 offset:1024
	ds_read_b128 v[160:163], v164 offset:2048
	ds_read_b128 v[164:167], v164 offset:3072
	ds_read_b128 v[168:171], v180
	ds_read_b128 v[172:175], v180 offset:1024
	ds_read_b128 v[176:179], v180 offset:2048
	ds_read_b128 v[180:183], v180 offset:3072
	s_add_u32 s38, s50, 0x80000
	s_addc_u32 s39, s51, 0
	s_mov_b32 m0, s55
	ds_read_b128 v[184:187], v151 offset:32768
	ds_read_b128 v[188:191], v151 offset:33792
	ds_read_b128 v[192:195], v151 offset:34816
	ds_read_b128 v[196:199], v151 offset:35840
	ds_read_b128 v[200:203], v151 offset:36864
	ds_read_b128 v[204:207], v151 offset:37888
	ds_read_b128 v[208:211], v151 offset:38912
	ds_read_b128 v[212:215], v151 offset:39936
	global_load_lds_dwordx4 v128, s[38:39]
	s_mov_b32 m0, s56
	s_nop 0
	global_load_lds_dwordx4 v132, s[38:39]
	s_waitcnt vmcnt(8)
	s_waitcnt lgkmcnt(0)
	s_barrier
	s_waitcnt lgkmcnt(0)
	v_mfma_f32_16x16x32_bf16 v[124:127], v[152:155], v[184:187], v[124:127]
	v_mfma_f32_16x16x32_bf16 v[120:123], v[160:163], v[184:187], v[120:123]
	v_mfma_f32_16x16x32_bf16 v[116:119], v[152:155], v[192:195], v[116:119]
	v_mfma_f32_16x16x32_bf16 v[108:111], v[160:163], v[192:195], v[108:111]
	v_mfma_f32_16x16x32_bf16 v[100:103], v[152:155], v[200:203], v[100:103]
	v_mfma_f32_16x16x32_bf16 v[92:95], v[160:163], v[200:203], v[92:95]
	v_mfma_f32_16x16x32_bf16 v[84:87], v[152:155], v[208:211], v[84:87]
	v_mfma_f32_16x16x32_bf16 v[76:79], v[160:163], v[208:211], v[76:79]
	v_mfma_f32_16x16x32_bf16 v[124:127], v[156:159], v[188:191], v[124:127]
	v_mfma_f32_16x16x32_bf16 v[120:123], v[164:167], v[188:191], v[120:123]
	v_mfma_f32_16x16x32_bf16 v[116:119], v[156:159], v[196:199], v[116:119]
	v_mfma_f32_16x16x32_bf16 v[108:111], v[164:167], v[196:199], v[108:111]
	v_mfma_f32_16x16x32_bf16 v[100:103], v[156:159], v[204:207], v[100:103]
	v_mfma_f32_16x16x32_bf16 v[92:95], v[164:167], v[204:207], v[92:95]
	v_mfma_f32_16x16x32_bf16 v[84:87], v[156:159], v[212:215], v[84:87]
	v_mfma_f32_16x16x32_bf16 v[76:79], v[164:167], v[212:215], v[76:79]
	v_mfma_f32_16x16x32_bf16 v[112:115], v[168:171], v[184:187], v[112:115]
	v_mfma_f32_16x16x32_bf16 v[104:107], v[176:179], v[184:187], v[104:107]
	v_mfma_f32_16x16x32_bf16 v[96:99], v[168:171], v[192:195], v[96:99]
	v_mfma_f32_16x16x32_bf16 v[88:91], v[176:179], v[192:195], v[88:91]
	v_mfma_f32_16x16x32_bf16 v[80:83], v[168:171], v[200:203], v[80:83]
	v_mfma_f32_16x16x32_bf16 v[72:75], v[176:179], v[200:203], v[72:75]
	v_mfma_f32_16x16x32_bf16 v[68:71], v[168:171], v[208:211], v[68:71]
	v_mfma_f32_16x16x32_bf16 v[64:67], v[176:179], v[208:211], v[64:67]
	v_mfma_f32_16x16x32_bf16 v[112:115], v[172:175], v[188:191], v[112:115]
	v_mfma_f32_16x16x32_bf16 v[104:107], v[180:183], v[188:191], v[104:107]
	v_mfma_f32_16x16x32_bf16 v[96:99], v[172:175], v[196:199], v[96:99]
	v_mfma_f32_16x16x32_bf16 v[88:91], v[180:183], v[196:199], v[88:91]
	v_mfma_f32_16x16x32_bf16 v[80:83], v[172:175], v[204:207], v[80:83]
	v_mfma_f32_16x16x32_bf16 v[72:75], v[180:183], v[204:207], v[72:75]
	v_mfma_f32_16x16x32_bf16 v[68:71], v[172:175], v[212:215], v[68:71]
	v_mfma_f32_16x16x32_bf16 v[64:67], v[180:183], v[212:215], v[64:67]
	s_barrier
	s_add_i32 s37, s37, s53
	s_mov_b32 m0, s37
	ds_read_b128 v[184:187], v151 offset:49152
	ds_read_b128 v[188:191], v151 offset:50176
	ds_read_b128 v[192:195], v151 offset:51200
	ds_read_b128 v[196:199], v151 offset:52224
	ds_read_b128 v[200:203], v151 offset:53248
	ds_read_b128 v[204:207], v151 offset:54272
	ds_read_b128 v[208:211], v151 offset:55296
	ds_read_b128 v[212:215], v151 offset:56320
	s_add_u32 s100, s48, 0x80
	s_addc_u32 s101, s49, 0
	global_load_lds_dwordx4 v130, s[100:101]
	s_add_i32 m0, s37, 0x2000
	s_add_u32 s38, s48, 0x80080
	s_addc_u32 s39, s49, 0
	s_add_i32 s37, s40, s53
	s_add_u32 s100, s48, 0x80
	s_addc_u32 s101, s49, 0
	global_load_lds_dwordx4 v134, s[100:101]
	s_mov_b32 m0, s37
	s_nop 0
	global_load_lds_dwordx4 v130, s[38:39]
	s_add_i32 m0, s37, 0x2000
	s_nop 0
	global_load_lds_dwordx4 v134, s[38:39]
	s_mov_b32 m0, s58
	s_nop 0
	s_add_u32 s100, s50, 0x80
	s_addc_u32 s101, s51, 0
	global_load_lds_dwordx4 v128, s[100:101]
	s_mov_b32 m0, s59
	s_nop 0
	s_add_u32 s100, s50, 0x80
	s_addc_u32 s101, s51, 0
	global_load_lds_dwordx4 v132, s[100:101]
	s_waitcnt vmcnt(8)
	s_waitcnt lgkmcnt(0)
	s_barrier
	s_waitcnt lgkmcnt(0)
	v_mfma_f32_16x16x32_bf16 v[60:63], v[152:155], v[184:187], v[60:63]
	v_mfma_f32_16x16x32_bf16 v[56:59], v[160:163], v[184:187], v[56:59]
	v_mfma_f32_16x16x32_bf16 v[52:55], v[152:155], v[192:195], v[52:55]
	v_mfma_f32_16x16x32_bf16 v[44:47], v[160:163], v[192:195], v[44:47]
	v_mfma_f32_16x16x32_bf16 v[36:39], v[152:155], v[200:203], v[36:39]
	v_mfma_f32_16x16x32_bf16 v[28:31], v[160:163], v[200:203], v[28:31]
	v_mfma_f32_16x16x32_bf16 v[20:23], v[152:155], v[208:211], v[20:23]
	v_mfma_f32_16x16x32_bf16 v[12:15], v[160:163], v[208:211], v[12:15]
	v_mfma_f32_16x16x32_bf16 v[60:63], v[156:159], v[188:191], v[60:63]
	v_mfma_f32_16x16x32_bf16 v[56:59], v[164:167], v[188:191], v[56:59]
	v_mfma_f32_16x16x32_bf16 v[52:55], v[156:159], v[196:199], v[52:55]
	v_mfma_f32_16x16x32_bf16 v[44:47], v[164:167], v[196:199], v[44:47]
	v_mfma_f32_16x16x32_bf16 v[36:39], v[156:159], v[204:207], v[36:39]
	v_mfma_f32_16x16x32_bf16 v[28:31], v[164:167], v[204:207], v[28:31]
	v_mfma_f32_16x16x32_bf16 v[20:23], v[156:159], v[212:215], v[20:23]
	v_mfma_f32_16x16x32_bf16 v[12:15], v[164:167], v[212:215], v[12:15]
	v_mfma_f32_16x16x32_bf16 v[48:51], v[168:171], v[184:187], v[48:51]
	v_mfma_f32_16x16x32_bf16 v[40:43], v[176:179], v[184:187], v[40:43]
	v_mfma_f32_16x16x32_bf16 v[32:35], v[168:171], v[192:195], v[32:35]
	v_mfma_f32_16x16x32_bf16 v[24:27], v[176:179], v[192:195], v[24:27]
	v_mfma_f32_16x16x32_bf16 v[16:19], v[168:171], v[200:203], v[16:19]
	v_mfma_f32_16x16x32_bf16 v[8:11], v[176:179], v[200:203], v[8:11]
	v_mfma_f32_16x16x32_bf16 v[4:7], v[168:171], v[208:211], v[4:7]
	v_mfma_f32_16x16x32_bf16 v[0:3], v[176:179], v[208:211], v[0:3]
	v_mfma_f32_16x16x32_bf16 v[48:51], v[172:175], v[188:191], v[48:51]
	v_mfma_f32_16x16x32_bf16 v[40:43], v[180:183], v[188:191], v[40:43]
	v_mfma_f32_16x16x32_bf16 v[32:35], v[172:175], v[196:199], v[32:35]
	v_mfma_f32_16x16x32_bf16 v[24:27], v[180:183], v[196:199], v[24:27]
	v_mfma_f32_16x16x32_bf16 v[16:19], v[172:175], v[204:207], v[16:19]
	v_mfma_f32_16x16x32_bf16 v[8:11], v[180:183], v[204:207], v[8:11]
	v_mfma_f32_16x16x32_bf16 v[4:7], v[172:175], v[212:215], v[4:7]
	v_mfma_f32_16x16x32_bf16 v[0:3], v[180:183], v[212:215], v[0:3]
	s_barrier
	s_add_i32 s36, s36, 2
	s_add_u32 s46, s46, 0x100
	s_addc_u32 s47, s47, 0
	s_add_u32 s34, s34, 0x100
	s_addc_u32 s35, s35, 0
	s_cmp_gt_u32 s36, 29
	s_cbranch_scc0 .LBB0_521
	s_setprio 0
	s_and_b64 vcc, exec, s[8:9]
	s_cbranch_vccz .LBB0_524
	s_barrier

.Lmy_prio_skip2:
.LBB0_600:
	ds_read_b128 v[152:155], v149
	ds_read_b128 v[156:159], v149 offset:1024
	ds_read_b128 v[160:163], v149 offset:2048
	ds_read_b128 v[164:167], v149 offset:3072
	ds_read_b128 v[168:171], v150
	ds_read_b128 v[172:175], v150 offset:1024
	ds_read_b128 v[176:179], v150 offset:2048
	ds_read_b128 v[180:183], v150 offset:3072
	s_add_u32 s37, s48, 0xfff00080
	s_addc_u32 s38, s49, -1
	s_cmp_eq_u32 s36, 60
	s_cselect_b32 s53, s17, s38
	s_cselect_b32 s52, s66, s37
	s_cselect_b32 s51, s13, s35
	s_cselect_b32 s50, s67, s34
	s_add_i32 m0, s19, 0xc000
	ds_read_b128 v[184:187], v151
	ds_read_b128 v[188:191], v151 offset:1024
	ds_read_b128 v[192:195], v151 offset:2048
	ds_read_b128 v[196:199], v151 offset:3072
	ds_read_b128 v[200:203], v151 offset:4096
	ds_read_b128 v[204:207], v151 offset:5120
	ds_read_b128 v[208:211], v151 offset:6144
	ds_read_b128 v[212:215], v151 offset:7168
	global_load_lds_dwordx4 v136, s[48:49]
	s_add_i32 m0, s19, 0xe000
	s_nop 0
	global_load_lds_dwordx4 v138, s[48:49]
	s_waitcnt vmcnt(8)
	s_waitcnt lgkmcnt(0)
	s_barrier
	s_waitcnt lgkmcnt(0)
	v_mfma_f32_16x16x32_bf16 v[124:127], v[152:155], v[184:187], v[124:127]
	v_mfma_f32_16x16x32_bf16 v[120:123], v[160:163], v[184:187], v[120:123]
	v_mfma_f32_16x16x32_bf16 v[116:119], v[152:155], v[192:195], v[116:119]
	v_mfma_f32_16x16x32_bf16 v[108:111], v[160:163], v[192:195], v[108:111]
	v_mfma_f32_16x16x32_bf16 v[100:103], v[152:155], v[200:203], v[100:103]
	v_mfma_f32_16x16x32_bf16 v[92:95], v[160:163], v[200:203], v[92:95]
	v_mfma_f32_16x16x32_bf16 v[84:87], v[152:155], v[208:211], v[84:87]
	v_mfma_f32_16x16x32_bf16 v[76:79], v[160:163], v[208:211], v[76:79]
	v_mfma_f32_16x16x32_bf16 v[124:127], v[156:159], v[188:191], v[124:127]
	v_mfma_f32_16x16x32_bf16 v[120:123], v[164:167], v[188:191], v[120:123]
	v_mfma_f32_16x16x32_bf16 v[116:119], v[156:159], v[196:199], v[116:119]
	v_mfma_f32_16x16x32_bf16 v[108:111], v[164:167], v[196:199], v[108:111]
	v_mfma_f32_16x16x32_bf16 v[100:103], v[156:159], v[204:207], v[100:103]
	v_mfma_f32_16x16x32_bf16 v[92:95], v[164:167], v[204:207], v[92:95]
	v_mfma_f32_16x16x32_bf16 v[84:87], v[156:159], v[212:215], v[84:87]
	v_mfma_f32_16x16x32_bf16 v[76:79], v[164:167], v[212:215], v[76:79]
	v_mfma_f32_16x16x32_bf16 v[112:115], v[168:171], v[184:187], v[112:115]
	v_mfma_f32_16x16x32_bf16 v[104:107], v[176:179], v[184:187], v[104:107]
	v_mfma_f32_16x16x32_bf16 v[96:99], v[168:171], v[192:195], v[96:99]
	v_mfma_f32_16x16x32_bf16 v[88:91], v[176:179], v[192:195], v[88:91]
	v_mfma_f32_16x16x32_bf16 v[80:83], v[168:171], v[200:203], v[80:83]
	v_mfma_f32_16x16x32_bf16 v[72:75], v[176:179], v[200:203], v[72:75]
	v_mfma_f32_16x16x32_bf16 v[68:71], v[168:171], v[208:211], v[68:71]
	v_mfma_f32_16x16x32_bf16 v[64:67], v[176:179], v[208:211], v[64:67]
	v_mfma_f32_16x16x32_bf16 v[112:115], v[172:175], v[188:191], v[112:115]
	v_mfma_f32_16x16x32_bf16 v[104:107], v[180:183], v[188:191], v[104:107]
	v_mfma_f32_16x16x32_bf16 v[96:99], v[172:175], v[196:199], v[96:99]
	v_mfma_f32_16x16x32_bf16 v[88:91], v[180:183], v[196:199], v[88:91]
	v_mfma_f32_16x16x32_bf16 v[80:83], v[172:175], v[204:207], v[80:83]
	v_mfma_f32_16x16x32_bf16 v[72:75], v[180:183], v[204:207], v[72:75]
	v_mfma_f32_16x16x32_bf16 v[68:71], v[172:175], v[212:215], v[68:71]
	v_mfma_f32_16x16x32_bf16 v[64:67], v[180:183], v[212:215], v[64:67]
	s_barrier
	s_add_i32 s37, s63, s55
	s_mov_b32 m0, s37
	ds_read_b128 v[184:187], v151 offset:16384
	ds_read_b128 v[188:191], v151 offset:17408
	ds_read_b128 v[192:195], v151 offset:18432
	ds_read_b128 v[196:199], v151 offset:19456
	ds_read_b128 v[200:203], v151 offset:20480
	ds_read_b128 v[204:207], v151 offset:21504
	ds_read_b128 v[208:211], v151 offset:22528
	ds_read_b128 v[212:215], v151 offset:23552
	global_load_lds_dwordx4 v130, s[50:51]
	s_add_i32 m0, s37, 0x2000
	s_add_u32 s38, s50, 0x100000
	s_addc_u32 s39, s51, 0
	s_add_i32 s37, s64, s55
	global_load_lds_dwordx4 v134, s[50:51]
	s_mov_b32 m0, s37
	global_load_lds_dwordx4 v130, s[38:39]
	s_add_i32 m0, s37, 0x2000
	s_nop 0
	global_load_lds_dwordx4 v134, s[38:39]
	s_mov_b32 m0, s19
	s_nop 0
	global_load_lds_dwordx4 v128, s[52:53]
	s_mov_b32 m0, s56
	s_nop 0
	global_load_lds_dwordx4 v132, s[52:53]
	s_waitcnt vmcnt(8)
	s_waitcnt lgkmcnt(0)
	s_barrier
	s_waitcnt lgkmcnt(0)
	v_mfma_f32_16x16x32_bf16 v[60:63], v[152:155], v[184:187], v[60:63]
	v_mfma_f32_16x16x32_bf16 v[56:59], v[160:163], v[184:187], v[56:59]
	v_mfma_f32_16x16x32_bf16 v[52:55], v[152:155], v[192:195], v[52:55]
	v_mfma_f32_16x16x32_bf16 v[44:47], v[160:163], v[192:195], v[44:47]
	v_mfma_f32_16x16x32_bf16 v[36:39], v[152:155], v[200:203], v[36:39]
	v_mfma_f32_16x16x32_bf16 v[28:31], v[160:163], v[200:203], v[28:31]
	v_mfma_f32_16x16x32_bf16 v[20:23], v[152:155], v[208:211], v[20:23]
	v_mfma_f32_16x16x32_bf16 v[12:15], v[160:163], v[208:211], v[12:15]
	v_mfma_f32_16x16x32_bf16 v[60:63], v[156:159], v[188:191], v[60:63]
	v_mfma_f32_16x16x32_bf16 v[56:59], v[164:167], v[188:191], v[56:59]
	v_mfma_f32_16x16x32_bf16 v[52:55], v[156:159], v[196:199], v[52:55]
	v_mfma_f32_16x16x32_bf16 v[44:47], v[164:167], v[196:199], v[44:47]
	v_mfma_f32_16x16x32_bf16 v[36:39], v[156:159], v[204:207], v[36:39]
	v_mfma_f32_16x16x32_bf16 v[28:31], v[164:167], v[204:207], v[28:31]
	v_mfma_f32_16x16x32_bf16 v[20:23], v[156:159], v[212:215], v[20:23]
	v_mfma_f32_16x16x32_bf16 v[12:15], v[164:167], v[212:215], v[12:15]
	v_mfma_f32_16x16x32_bf16 v[48:51], v[168:171], v[184:187], v[48:51]
	v_mfma_f32_16x16x32_bf16 v[40:43], v[176:179], v[184:187], v[40:43]
	v_mfma_f32_16x16x32_bf16 v[32:35], v[168:171], v[192:195], v[32:35]
	v_mfma_f32_16x16x32_bf16 v[24:27], v[176:179], v[192:195], v[24:27]
	v_mfma_f32_16x16x32_bf16 v[16:19], v[168:171], v[200:203], v[16:19]
	v_mfma_f32_16x16x32_bf16 v[8:11], v[176:179], v[200:203], v[8:11]
	v_mfma_f32_16x16x32_bf16 v[4:7], v[168:171], v[208:211], v[4:7]
	v_mfma_f32_16x16x32_bf16 v[0:3], v[176:179], v[208:211], v[0:3]
	v_mfma_f32_16x16x32_bf16 v[48:51], v[172:175], v[188:191], v[48:51]
	v_mfma_f32_16x16x32_bf16 v[40:43], v[180:183], v[188:191], v[40:43]
	v_mfma_f32_16x16x32_bf16 v[32:35], v[172:175], v[196:199], v[32:35]
	v_mfma_f32_16x16x32_bf16 v[24:27], v[180:183], v[196:199], v[24:27]
	v_mfma_f32_16x16x32_bf16 v[16:19], v[172:175], v[204:207], v[16:19]
	v_mfma_f32_16x16x32_bf16 v[8:11], v[180:183], v[204:207], v[8:11]
	v_mfma_f32_16x16x32_bf16 v[4:7], v[172:175], v[212:215], v[4:7]
	v_mfma_f32_16x16x32_bf16 v[0:3], v[180:183], v[212:215], v[0:3]
	s_barrier
	s_add_i32 s37, 0, 0x18000
	s_add_i32 s40, 0, 0x1c000
	v_add_u32_e32 v164, s37, v147
	v_add_u32_e32 v180, s40, v147
	ds_read_b128 v[152:155], v164
	ds_read_b128 v[156:159], v164 offset:1024
	ds_read_b128 v[160:163], v164 offset:2048
	ds_read_b128 v[164:167], v164 offset:3072
	ds_read_b128 v[168:171], v180
	ds_read_b128 v[172:175], v180 offset:1024
	ds_read_b128 v[176:179], v180 offset:2048
	ds_read_b128 v[180:183], v180 offset:3072
	s_add_u32 s38, s52, 0x100000
	s_addc_u32 s39, s53, 0
	s_mov_b32 m0, s57
	ds_read_b128 v[184:187], v151 offset:32768
	ds_read_b128 v[188:191], v151 offset:33792
	ds_read_b128 v[192:195], v151 offset:34816
	ds_read_b128 v[196:199], v151 offset:35840
	ds_read_b128 v[200:203], v151 offset:36864
	ds_read_b128 v[204:207], v151 offset:37888
	ds_read_b128 v[208:211], v151 offset:38912
	ds_read_b128 v[212:215], v151 offset:39936
	global_load_lds_dwordx4 v128, s[38:39]
	s_mov_b32 m0, s58
	s_nop 0
	global_load_lds_dwordx4 v132, s[38:39]
	s_waitcnt vmcnt(8)
	s_waitcnt lgkmcnt(0)
	s_barrier
	s_waitcnt lgkmcnt(0)
	v_mfma_f32_16x16x32_bf16 v[124:127], v[152:155], v[184:187], v[124:127]
	v_mfma_f32_16x16x32_bf16 v[120:123], v[160:163], v[184:187], v[120:123]
	v_mfma_f32_16x16x32_bf16 v[116:119], v[152:155], v[192:195], v[116:119]
	v_mfma_f32_16x16x32_bf16 v[108:111], v[160:163], v[192:195], v[108:111]
	v_mfma_f32_16x16x32_bf16 v[100:103], v[152:155], v[200:203], v[100:103]
	v_mfma_f32_16x16x32_bf16 v[92:95], v[160:163], v[200:203], v[92:95]
	v_mfma_f32_16x16x32_bf16 v[84:87], v[152:155], v[208:211], v[84:87]
	v_mfma_f32_16x16x32_bf16 v[76:79], v[160:163], v[208:211], v[76:79]
	v_mfma_f32_16x16x32_bf16 v[124:127], v[156:159], v[188:191], v[124:127]
	v_mfma_f32_16x16x32_bf16 v[120:123], v[164:167], v[188:191], v[120:123]
	v_mfma_f32_16x16x32_bf16 v[116:119], v[156:159], v[196:199], v[116:119]
	v_mfma_f32_16x16x32_bf16 v[108:111], v[164:167], v[196:199], v[108:111]
	v_mfma_f32_16x16x32_bf16 v[100:103], v[156:159], v[204:207], v[100:103]
	v_mfma_f32_16x16x32_bf16 v[92:95], v[164:167], v[204:207], v[92:95]
	v_mfma_f32_16x16x32_bf16 v[84:87], v[156:159], v[212:215], v[84:87]
	v_mfma_f32_16x16x32_bf16 v[76:79], v[164:167], v[212:215], v[76:79]
	v_mfma_f32_16x16x32_bf16 v[112:115], v[168:171], v[184:187], v[112:115]
	v_mfma_f32_16x16x32_bf16 v[104:107], v[176:179], v[184:187], v[104:107]
	v_mfma_f32_16x16x32_bf16 v[96:99], v[168:171], v[192:195], v[96:99]
	v_mfma_f32_16x16x32_bf16 v[88:91], v[176:179], v[192:195], v[88:91]
	v_mfma_f32_16x16x32_bf16 v[80:83], v[168:171], v[200:203], v[80:83]
	v_mfma_f32_16x16x32_bf16 v[72:75], v[176:179], v[200:203], v[72:75]
	v_mfma_f32_16x16x32_bf16 v[68:71], v[168:171], v[208:211], v[68:71]
	v_mfma_f32_16x16x32_bf16 v[64:67], v[176:179], v[208:211], v[64:67]
	v_mfma_f32_16x16x32_bf16 v[112:115], v[172:175], v[188:191], v[112:115]
	v_mfma_f32_16x16x32_bf16 v[104:107], v[180:183], v[188:191], v[104:107]
	v_mfma_f32_16x16x32_bf16 v[96:99], v[172:175], v[196:199], v[96:99]
	v_mfma_f32_16x16x32_bf16 v[88:91], v[180:183], v[196:199], v[88:91]
	v_mfma_f32_16x16x32_bf16 v[80:83], v[172:175], v[204:207], v[80:83]
	v_mfma_f32_16x16x32_bf16 v[72:75], v[180:183], v[204:207], v[72:75]
	v_mfma_f32_16x16x32_bf16 v[68:71], v[172:175], v[212:215], v[68:71]
	v_mfma_f32_16x16x32_bf16 v[64:67], v[180:183], v[212:215], v[64:67]
	s_barrier
	s_add_i32 s37, s37, s55
	s_mov_b32 m0, s37
	ds_read_b128 v[184:187], v151 offset:49152
	ds_read_b128 v[188:191], v151 offset:50176
	ds_read_b128 v[192:195], v151 offset:51200
	ds_read_b128 v[196:199], v151 offset:52224
	ds_read_b128 v[200:203], v151 offset:53248
	ds_read_b128 v[204:207], v151 offset:54272
	ds_read_b128 v[208:211], v151 offset:55296
	ds_read_b128 v[212:215], v151 offset:56320
	s_add_u32 s100, s50, 0x80
	s_addc_u32 s101, s51, 0
	global_load_lds_dwordx4 v130, s[100:101]
	s_add_i32 m0, s37, 0x2000
	s_add_u32 s38, s50, 0x100080
	s_addc_u32 s39, s51, 0
	s_add_i32 s37, s40, s55
	s_add_u32 s100, s50, 0x80
	s_addc_u32 s101, s51, 0
	global_load_lds_dwordx4 v134, s[100:101]
	s_mov_b32 m0, s37
	s_nop 0
	global_load_lds_dwordx4 v130, s[38:39]
	s_add_i32 m0, s37, 0x2000
	s_nop 0
	global_load_lds_dwordx4 v134, s[38:39]
	s_mov_b32 m0, s60
	s_nop 0
	s_add_u32 s100, s52, 0x80
	s_addc_u32 s101, s53, 0
	global_load_lds_dwordx4 v128, s[100:101]
	s_mov_b32 m0, s61
	s_nop 0
	s_add_u32 s100, s52, 0x80
	s_addc_u32 s101, s53, 0
	global_load_lds_dwordx4 v132, s[100:101]
	s_waitcnt vmcnt(8)
	s_waitcnt lgkmcnt(0)
	s_barrier
	s_waitcnt lgkmcnt(0)
	v_mfma_f32_16x16x32_bf16 v[60:63], v[152:155], v[184:187], v[60:63]
	v_mfma_f32_16x16x32_bf16 v[56:59], v[160:163], v[184:187], v[56:59]
	v_mfma_f32_16x16x32_bf16 v[52:55], v[152:155], v[192:195], v[52:55]
	v_mfma_f32_16x16x32_bf16 v[44:47], v[160:163], v[192:195], v[44:47]
	v_mfma_f32_16x16x32_bf16 v[36:39], v[152:155], v[200:203], v[36:39]
	v_mfma_f32_16x16x32_bf16 v[28:31], v[160:163], v[200:203], v[28:31]
	v_mfma_f32_16x16x32_bf16 v[20:23], v[152:155], v[208:211], v[20:23]
	v_mfma_f32_16x16x32_bf16 v[12:15], v[160:163], v[208:211], v[12:15]
	v_mfma_f32_16x16x32_bf16 v[60:63], v[156:159], v[188:191], v[60:63]
	v_mfma_f32_16x16x32_bf16 v[56:59], v[164:167], v[188:191], v[56:59]
	v_mfma_f32_16x16x32_bf16 v[52:55], v[156:159], v[196:199], v[52:55]
	v_mfma_f32_16x16x32_bf16 v[44:47], v[164:167], v[196:199], v[44:47]
	v_mfma_f32_16x16x32_bf16 v[36:39], v[156:159], v[204:207], v[36:39]
	v_mfma_f32_16x16x32_bf16 v[28:31], v[164:167], v[204:207], v[28:31]
	v_mfma_f32_16x16x32_bf16 v[20:23], v[156:159], v[212:215], v[20:23]
	v_mfma_f32_16x16x32_bf16 v[12:15], v[164:167], v[212:215], v[12:15]
	v_mfma_f32_16x16x32_bf16 v[48:51], v[168:171], v[184:187], v[48:51]
	v_mfma_f32_16x16x32_bf16 v[40:43], v[176:179], v[184:187], v[40:43]
	v_mfma_f32_16x16x32_bf16 v[32:35], v[168:171], v[192:195], v[32:35]
	v_mfma_f32_16x16x32_bf16 v[24:27], v[176:179], v[192:195], v[24:27]
	v_mfma_f32_16x16x32_bf16 v[16:19], v[168:171], v[200:203], v[16:19]
	v_mfma_f32_16x16x32_bf16 v[8:11], v[176:179], v[200:203], v[8:11]
	v_mfma_f32_16x16x32_bf16 v[4:7], v[168:171], v[208:211], v[4:7]
	v_mfma_f32_16x16x32_bf16 v[0:3], v[176:179], v[208:211], v[0:3]
	v_mfma_f32_16x16x32_bf16 v[48:51], v[172:175], v[188:191], v[48:51]
	v_mfma_f32_16x16x32_bf16 v[40:43], v[180:183], v[188:191], v[40:43]
	v_mfma_f32_16x16x32_bf16 v[32:35], v[172:175], v[196:199], v[32:35]
	v_mfma_f32_16x16x32_bf16 v[24:27], v[180:183], v[196:199], v[24:27]
	v_mfma_f32_16x16x32_bf16 v[16:19], v[172:175], v[204:207], v[16:19]
	v_mfma_f32_16x16x32_bf16 v[8:11], v[180:183], v[204:207], v[8:11]
	v_mfma_f32_16x16x32_bf16 v[4:7], v[172:175], v[212:215], v[4:7]
	v_mfma_f32_16x16x32_bf16 v[0:3], v[180:183], v[212:215], v[0:3]
	s_barrier
	s_add_i32 s36, s36, 2
	s_add_u32 s48, s48, 0x100
	s_addc_u32 s49, s49, 0
	s_add_u32 s34, s34, 0x100
	s_addc_u32 s35, s35, 0
	s_cmp_gt_u32 s36, 61
	s_cbranch_scc0 .LBB0_600
	s_setprio 0
	s_and_b64 vcc, exec, s[10:11]
	s_cbranch_vccz .LBB0_603
	s_barrier

.Lmy_prio_skip3:
.LBB0_679:
	ds_read_b128 v[144:147], v151
	ds_read_b128 v[154:157], v151 offset:1024
	ds_read_b128 v[158:161], v151 offset:2048
	ds_read_b128 v[162:165], v151 offset:3072
	ds_read_b128 v[166:169], v152
	ds_read_b128 v[170:173], v152 offset:1024
	ds_read_b128 v[174:177], v152 offset:2048
	ds_read_b128 v[178:181], v152 offset:3072
	s_add_u32 s37, s50, 0xfff00080
	s_addc_u32 s38, s51, -1
	s_cmp_eq_u32 s36, 60
	s_cselect_b32 s55, s19, s38
	s_cselect_b32 s54, s66, s37
	s_cselect_b32 s53, s17, s35
	s_cselect_b32 s52, s67, s34
	s_add_i32 m0, s49, 0xc000
	ds_read_b128 v[182:185], v153
	ds_read_b128 v[186:189], v153 offset:1024
	ds_read_b128 v[190:193], v153 offset:2048
	ds_read_b128 v[194:197], v153 offset:3072
	ds_read_b128 v[198:201], v153 offset:4096
	ds_read_b128 v[202:205], v153 offset:5120
	ds_read_b128 v[206:209], v153 offset:6144
	ds_read_b128 v[210:213], v153 offset:7168
	global_load_lds_dwordx4 v136, s[50:51]
	s_add_i32 m0, s49, 0xe000
	s_nop 0
	global_load_lds_dwordx4 v138, s[50:51]
	s_waitcnt vmcnt(8)
	s_waitcnt lgkmcnt(0)
	s_barrier
	s_waitcnt lgkmcnt(0)
	v_mfma_f32_16x16x32_bf16 v[124:127], v[144:147], v[182:185], v[124:127]
	v_mfma_f32_16x16x32_bf16 v[116:119], v[158:161], v[182:185], v[116:119]
	v_mfma_f32_16x16x32_bf16 v[108:111], v[144:147], v[190:193], v[108:111]
	v_mfma_f32_16x16x32_bf16 v[104:107], v[158:161], v[190:193], v[104:107]
	v_mfma_f32_16x16x32_bf16 v[92:95], v[144:147], v[198:201], v[92:95]
	v_mfma_f32_16x16x32_bf16 v[88:91], v[158:161], v[198:201], v[88:91]
	v_mfma_f32_16x16x32_bf16 v[76:79], v[144:147], v[206:209], v[76:79]
	v_mfma_f32_16x16x32_bf16 v[72:75], v[158:161], v[206:209], v[72:75]
	v_mfma_f32_16x16x32_bf16 v[124:127], v[154:157], v[186:189], v[124:127]
	v_mfma_f32_16x16x32_bf16 v[116:119], v[162:165], v[186:189], v[116:119]
	v_mfma_f32_16x16x32_bf16 v[108:111], v[154:157], v[194:197], v[108:111]
	v_mfma_f32_16x16x32_bf16 v[104:107], v[162:165], v[194:197], v[104:107]
	v_mfma_f32_16x16x32_bf16 v[92:95], v[154:157], v[202:205], v[92:95]
	v_mfma_f32_16x16x32_bf16 v[88:91], v[162:165], v[202:205], v[88:91]
	v_mfma_f32_16x16x32_bf16 v[76:79], v[154:157], v[210:213], v[76:79]
	v_mfma_f32_16x16x32_bf16 v[72:75], v[162:165], v[210:213], v[72:75]
	v_mfma_f32_16x16x32_bf16 v[120:123], v[166:169], v[182:185], v[120:123]
	v_mfma_f32_16x16x32_bf16 v[112:115], v[174:177], v[182:185], v[112:115]
	v_mfma_f32_16x16x32_bf16 v[100:103], v[166:169], v[190:193], v[100:103]
	v_mfma_f32_16x16x32_bf16 v[96:99], v[174:177], v[190:193], v[96:99]
	v_mfma_f32_16x16x32_bf16 v[84:87], v[166:169], v[198:201], v[84:87]
	v_mfma_f32_16x16x32_bf16 v[80:83], v[174:177], v[198:201], v[80:83]
	v_mfma_f32_16x16x32_bf16 v[68:71], v[166:169], v[206:209], v[68:71]
	v_mfma_f32_16x16x32_bf16 v[64:67], v[174:177], v[206:209], v[64:67]
	v_mfma_f32_16x16x32_bf16 v[120:123], v[170:173], v[186:189], v[120:123]
	v_mfma_f32_16x16x32_bf16 v[112:115], v[178:181], v[186:189], v[112:115]
	v_mfma_f32_16x16x32_bf16 v[100:103], v[170:173], v[194:197], v[100:103]
	v_mfma_f32_16x16x32_bf16 v[96:99], v[178:181], v[194:197], v[96:99]
	v_mfma_f32_16x16x32_bf16 v[84:87], v[170:173], v[202:205], v[84:87]
	v_mfma_f32_16x16x32_bf16 v[80:83], v[178:181], v[202:205], v[80:83]
	v_mfma_f32_16x16x32_bf16 v[68:71], v[170:173], v[210:213], v[68:71]
	v_mfma_f32_16x16x32_bf16 v[64:67], v[178:181], v[210:213], v[64:67]
	s_barrier
	s_add_i32 s37, s63, s33
	s_mov_b32 m0, s37
	ds_read_b128 v[182:185], v153 offset:16384
	ds_read_b128 v[186:189], v153 offset:17408
	ds_read_b128 v[190:193], v153 offset:18432
	ds_read_b128 v[194:197], v153 offset:19456
	ds_read_b128 v[198:201], v153 offset:20480
	ds_read_b128 v[202:205], v153 offset:21504
	ds_read_b128 v[206:209], v153 offset:22528
	ds_read_b128 v[210:213], v153 offset:23552
	global_load_lds_dwordx4 v130, s[52:53]
	s_add_i32 m0, s37, 0x2000
	s_add_u32 s38, s52, 0x100000
	s_addc_u32 s39, s53, 0
	s_add_i32 s37, s64, s33
	global_load_lds_dwordx4 v134, s[52:53]
	s_mov_b32 m0, s37
	global_load_lds_dwordx4 v130, s[38:39]
	s_add_i32 m0, s37, 0x2000
	s_nop 0
	global_load_lds_dwordx4 v134, s[38:39]
	s_mov_b32 m0, s49
	s_nop 0
	global_load_lds_dwordx4 v128, s[54:55]
	s_mov_b32 m0, s56
	s_nop 0
	global_load_lds_dwordx4 v132, s[54:55]
	s_waitcnt vmcnt(8)
	s_waitcnt lgkmcnt(0)
	s_barrier
	s_waitcnt lgkmcnt(0)
	v_mfma_f32_16x16x32_bf16 v[60:63], v[144:147], v[182:185], v[60:63]
	v_mfma_f32_16x16x32_bf16 v[56:59], v[158:161], v[182:185], v[56:59]
	v_mfma_f32_16x16x32_bf16 v[44:47], v[144:147], v[190:193], v[44:47]
	v_mfma_f32_16x16x32_bf16 v[40:43], v[158:161], v[190:193], v[40:43]
	v_mfma_f32_16x16x32_bf16 v[28:31], v[144:147], v[198:201], v[28:31]
	v_mfma_f32_16x16x32_bf16 v[24:27], v[158:161], v[198:201], v[24:27]
	v_mfma_f32_16x16x32_bf16 v[12:15], v[144:147], v[206:209], v[12:15]
	v_mfma_f32_16x16x32_bf16 v[8:11], v[158:161], v[206:209], v[8:11]
	v_mfma_f32_16x16x32_bf16 v[60:63], v[154:157], v[186:189], v[60:63]
	v_mfma_f32_16x16x32_bf16 v[56:59], v[162:165], v[186:189], v[56:59]
	v_mfma_f32_16x16x32_bf16 v[44:47], v[154:157], v[194:197], v[44:47]
	v_mfma_f32_16x16x32_bf16 v[40:43], v[162:165], v[194:197], v[40:43]
	v_mfma_f32_16x16x32_bf16 v[28:31], v[154:157], v[202:205], v[28:31]
	v_mfma_f32_16x16x32_bf16 v[24:27], v[162:165], v[202:205], v[24:27]
	v_mfma_f32_16x16x32_bf16 v[12:15], v[154:157], v[210:213], v[12:15]
	v_mfma_f32_16x16x32_bf16 v[8:11], v[162:165], v[210:213], v[8:11]
	v_mfma_f32_16x16x32_bf16 v[52:55], v[166:169], v[182:185], v[52:55]
	v_mfma_f32_16x16x32_bf16 v[48:51], v[174:177], v[182:185], v[48:51]
	v_mfma_f32_16x16x32_bf16 v[36:39], v[166:169], v[190:193], v[36:39]
	v_mfma_f32_16x16x32_bf16 v[32:35], v[174:177], v[190:193], v[32:35]
	v_mfma_f32_16x16x32_bf16 v[20:23], v[166:169], v[198:201], v[20:23]
	v_mfma_f32_16x16x32_bf16 v[16:19], v[174:177], v[198:201], v[16:19]
	v_mfma_f32_16x16x32_bf16 v[4:7], v[166:169], v[206:209], v[4:7]
	v_mfma_f32_16x16x32_bf16 v[0:3], v[174:177], v[206:209], v[0:3]
	v_mfma_f32_16x16x32_bf16 v[52:55], v[170:173], v[186:189], v[52:55]
	v_mfma_f32_16x16x32_bf16 v[48:51], v[178:181], v[186:189], v[48:51]
	v_mfma_f32_16x16x32_bf16 v[36:39], v[170:173], v[194:197], v[36:39]
	v_mfma_f32_16x16x32_bf16 v[32:35], v[178:181], v[194:197], v[32:35]
	v_mfma_f32_16x16x32_bf16 v[20:23], v[170:173], v[202:205], v[20:23]
	v_mfma_f32_16x16x32_bf16 v[16:19], v[178:181], v[202:205], v[16:19]
	v_mfma_f32_16x16x32_bf16 v[4:7], v[170:173], v[210:213], v[4:7]
	v_mfma_f32_16x16x32_bf16 v[0:3], v[178:181], v[210:213], v[0:3]
	s_barrier
	s_add_i32 s37, 0, 0x18000
	s_add_i32 s40, 0, 0x1c000
	v_add_u32_e32 v162, s37, v149
	v_add_u32_e32 v178, s40, v149
	ds_read_b128 v[144:147], v162
	ds_read_b128 v[154:157], v162 offset:1024
	ds_read_b128 v[158:161], v162 offset:2048
	ds_read_b128 v[162:165], v162 offset:3072
	ds_read_b128 v[166:169], v178
	ds_read_b128 v[170:173], v178 offset:1024
	ds_read_b128 v[174:177], v178 offset:2048
	ds_read_b128 v[178:181], v178 offset:3072
	s_add_u32 s38, s54, 0x100000
	s_addc_u32 s39, s55, 0
	s_mov_b32 m0, s57
	ds_read_b128 v[182:185], v153 offset:32768
	ds_read_b128 v[186:189], v153 offset:33792
	ds_read_b128 v[190:193], v153 offset:34816
	ds_read_b128 v[194:197], v153 offset:35840
	ds_read_b128 v[198:201], v153 offset:36864
	ds_read_b128 v[202:205], v153 offset:37888
	ds_read_b128 v[206:209], v153 offset:38912
	ds_read_b128 v[210:213], v153 offset:39936
	global_load_lds_dwordx4 v128, s[38:39]
	s_mov_b32 m0, s58
	s_nop 0
	global_load_lds_dwordx4 v132, s[38:39]
	s_waitcnt vmcnt(8)
	s_waitcnt lgkmcnt(0)
	s_barrier
	s_waitcnt lgkmcnt(0)
	v_mfma_f32_16x16x32_bf16 v[124:127], v[144:147], v[182:185], v[124:127]
	v_mfma_f32_16x16x32_bf16 v[116:119], v[158:161], v[182:185], v[116:119]
	v_mfma_f32_16x16x32_bf16 v[108:111], v[144:147], v[190:193], v[108:111]
	v_mfma_f32_16x16x32_bf16 v[104:107], v[158:161], v[190:193], v[104:107]
	v_mfma_f32_16x16x32_bf16 v[92:95], v[144:147], v[198:201], v[92:95]
	v_mfma_f32_16x16x32_bf16 v[88:91], v[158:161], v[198:201], v[88:91]
	v_mfma_f32_16x16x32_bf16 v[76:79], v[144:147], v[206:209], v[76:79]
	v_mfma_f32_16x16x32_bf16 v[72:75], v[158:161], v[206:209], v[72:75]
	v_mfma_f32_16x16x32_bf16 v[124:127], v[154:157], v[186:189], v[124:127]
	v_mfma_f32_16x16x32_bf16 v[116:119], v[162:165], v[186:189], v[116:119]
	v_mfma_f32_16x16x32_bf16 v[108:111], v[154:157], v[194:197], v[108:111]
	v_mfma_f32_16x16x32_bf16 v[104:107], v[162:165], v[194:197], v[104:107]
	v_mfma_f32_16x16x32_bf16 v[92:95], v[154:157], v[202:205], v[92:95]
	v_mfma_f32_16x16x32_bf16 v[88:91], v[162:165], v[202:205], v[88:91]
	v_mfma_f32_16x16x32_bf16 v[76:79], v[154:157], v[210:213], v[76:79]
	v_mfma_f32_16x16x32_bf16 v[72:75], v[162:165], v[210:213], v[72:75]
	v_mfma_f32_16x16x32_bf16 v[120:123], v[166:169], v[182:185], v[120:123]
	v_mfma_f32_16x16x32_bf16 v[112:115], v[174:177], v[182:185], v[112:115]
	v_mfma_f32_16x16x32_bf16 v[100:103], v[166:169], v[190:193], v[100:103]
	v_mfma_f32_16x16x32_bf16 v[96:99], v[174:177], v[190:193], v[96:99]
	v_mfma_f32_16x16x32_bf16 v[84:87], v[166:169], v[198:201], v[84:87]
	v_mfma_f32_16x16x32_bf16 v[80:83], v[174:177], v[198:201], v[80:83]
	v_mfma_f32_16x16x32_bf16 v[68:71], v[166:169], v[206:209], v[68:71]
	v_mfma_f32_16x16x32_bf16 v[64:67], v[174:177], v[206:209], v[64:67]
	v_mfma_f32_16x16x32_bf16 v[120:123], v[170:173], v[186:189], v[120:123]
	v_mfma_f32_16x16x32_bf16 v[112:115], v[178:181], v[186:189], v[112:115]
	v_mfma_f32_16x16x32_bf16 v[100:103], v[170:173], v[194:197], v[100:103]
	v_mfma_f32_16x16x32_bf16 v[96:99], v[178:181], v[194:197], v[96:99]
	v_mfma_f32_16x16x32_bf16 v[84:87], v[170:173], v[202:205], v[84:87]
	v_mfma_f32_16x16x32_bf16 v[80:83], v[178:181], v[202:205], v[80:83]
	v_mfma_f32_16x16x32_bf16 v[68:71], v[170:173], v[210:213], v[68:71]
	v_mfma_f32_16x16x32_bf16 v[64:67], v[178:181], v[210:213], v[64:67]
	s_barrier
	s_add_i32 s37, s37, s33
	s_mov_b32 m0, s37
	ds_read_b128 v[182:185], v153 offset:49152
	ds_read_b128 v[186:189], v153 offset:50176
	ds_read_b128 v[190:193], v153 offset:51200
	ds_read_b128 v[194:197], v153 offset:52224
	ds_read_b128 v[198:201], v153 offset:53248
	ds_read_b128 v[202:205], v153 offset:54272
	ds_read_b128 v[206:209], v153 offset:55296
	ds_read_b128 v[210:213], v153 offset:56320
	s_add_u32 s100, s52, 0x80
	s_addc_u32 s101, s53, 0
	global_load_lds_dwordx4 v130, s[100:101]
	s_add_i32 m0, s37, 0x2000
	s_add_u32 s38, s52, 0x100080
	s_addc_u32 s39, s53, 0
	s_add_i32 s37, s40, s33
	s_add_u32 s100, s52, 0x80
	s_addc_u32 s101, s53, 0
	global_load_lds_dwordx4 v134, s[100:101]
	s_mov_b32 m0, s37
	s_nop 0
	global_load_lds_dwordx4 v130, s[38:39]
	s_add_i32 m0, s37, 0x2000
	s_nop 0
	global_load_lds_dwordx4 v134, s[38:39]
	s_mov_b32 m0, s60
	s_nop 0
	s_add_u32 s100, s54, 0x80
	s_addc_u32 s101, s55, 0
	global_load_lds_dwordx4 v128, s[100:101]
	s_mov_b32 m0, s61
	s_nop 0
	s_add_u32 s100, s54, 0x80
	s_addc_u32 s101, s55, 0
	global_load_lds_dwordx4 v132, s[100:101]
	s_waitcnt vmcnt(8)
	s_waitcnt lgkmcnt(0)
	s_barrier
	s_waitcnt lgkmcnt(0)
	v_mfma_f32_16x16x32_bf16 v[60:63], v[144:147], v[182:185], v[60:63]
	v_mfma_f32_16x16x32_bf16 v[56:59], v[158:161], v[182:185], v[56:59]
	v_mfma_f32_16x16x32_bf16 v[44:47], v[144:147], v[190:193], v[44:47]
	v_mfma_f32_16x16x32_bf16 v[40:43], v[158:161], v[190:193], v[40:43]
	v_mfma_f32_16x16x32_bf16 v[28:31], v[144:147], v[198:201], v[28:31]
	v_mfma_f32_16x16x32_bf16 v[24:27], v[158:161], v[198:201], v[24:27]
	v_mfma_f32_16x16x32_bf16 v[12:15], v[144:147], v[206:209], v[12:15]
	v_mfma_f32_16x16x32_bf16 v[8:11], v[158:161], v[206:209], v[8:11]
	v_mfma_f32_16x16x32_bf16 v[60:63], v[154:157], v[186:189], v[60:63]
	v_mfma_f32_16x16x32_bf16 v[56:59], v[162:165], v[186:189], v[56:59]
	v_mfma_f32_16x16x32_bf16 v[44:47], v[154:157], v[194:197], v[44:47]
	v_mfma_f32_16x16x32_bf16 v[40:43], v[162:165], v[194:197], v[40:43]
	v_mfma_f32_16x16x32_bf16 v[28:31], v[154:157], v[202:205], v[28:31]
	v_mfma_f32_16x16x32_bf16 v[24:27], v[162:165], v[202:205], v[24:27]
	v_mfma_f32_16x16x32_bf16 v[12:15], v[154:157], v[210:213], v[12:15]
	v_mfma_f32_16x16x32_bf16 v[8:11], v[162:165], v[210:213], v[8:11]
	v_mfma_f32_16x16x32_bf16 v[52:55], v[166:169], v[182:185], v[52:55]
	v_mfma_f32_16x16x32_bf16 v[48:51], v[174:177], v[182:185], v[48:51]
	v_mfma_f32_16x16x32_bf16 v[36:39], v[166:169], v[190:193], v[36:39]
	v_mfma_f32_16x16x32_bf16 v[32:35], v[174:177], v[190:193], v[32:35]
	v_mfma_f32_16x16x32_bf16 v[20:23], v[166:169], v[198:201], v[20:23]
	v_mfma_f32_16x16x32_bf16 v[16:19], v[174:177], v[198:201], v[16:19]
	v_mfma_f32_16x16x32_bf16 v[4:7], v[166:169], v[206:209], v[4:7]
	v_mfma_f32_16x16x32_bf16 v[0:3], v[174:177], v[206:209], v[0:3]
	v_mfma_f32_16x16x32_bf16 v[52:55], v[170:173], v[186:189], v[52:55]
	v_mfma_f32_16x16x32_bf16 v[48:51], v[178:181], v[186:189], v[48:51]
	v_mfma_f32_16x16x32_bf16 v[36:39], v[170:173], v[194:197], v[36:39]
	v_mfma_f32_16x16x32_bf16 v[32:35], v[178:181], v[194:197], v[32:35]
	v_mfma_f32_16x16x32_bf16 v[20:23], v[170:173], v[202:205], v[20:23]
	v_mfma_f32_16x16x32_bf16 v[16:19], v[178:181], v[202:205], v[16:19]
	v_mfma_f32_16x16x32_bf16 v[4:7], v[170:173], v[210:213], v[4:7]
	v_mfma_f32_16x16x32_bf16 v[0:3], v[178:181], v[210:213], v[0:3]
	s_barrier
	s_add_i32 s36, s36, 2
	s_add_u32 s50, s50, 0x100
	s_addc_u32 s51, s51, 0
	s_add_u32 s34, s34, 0x100
	s_addc_u32 s35, s35, 0
	s_cmp_gt_u32 s36, 61
	s_cbranch_scc0 .LBB0_679
	s_setprio 0
	s_and_b64 vcc, exec, s[12:13]
	s_cbranch_vccz .LBB0_682
	s_barrier

.Lmy_prio_skip4:
.LBB0_758:
	ds_read_b128 v[144:147], v153
	ds_read_b128 v[156:159], v153 offset:1024
	ds_read_b128 v[160:163], v153 offset:2048
	ds_read_b128 v[164:167], v153 offset:3072
	ds_read_b128 v[168:171], v154
	ds_read_b128 v[172:175], v154 offset:1024
	ds_read_b128 v[176:179], v154 offset:2048
	ds_read_b128 v[180:183], v154 offset:3072
	s_add_u32 s37, s38, 0xfff00080
	s_addc_u32 s40, s39, -1
	s_cmp_eq_u32 s36, 60
	s_cselect_b32 s49, s13, s40
	s_cselect_b32 s48, s64, s37
	s_cselect_b32 s47, s11, s35
	s_cselect_b32 s46, s65, s34
	s_add_i32 m0, s76, 0xc000
	ds_read_b128 v[184:187], v155
	ds_read_b128 v[188:191], v155 offset:1024
	ds_read_b128 v[192:195], v155 offset:2048
	ds_read_b128 v[196:199], v155 offset:3072
	ds_read_b128 v[200:203], v155 offset:4096
	ds_read_b128 v[204:207], v155 offset:5120
	ds_read_b128 v[208:211], v155 offset:6144
	ds_read_b128 v[212:215], v155 offset:7168
	global_load_lds_dwordx4 v136, s[38:39]
	s_add_i32 m0, s76, 0xe000
	s_nop 0
	global_load_lds_dwordx4 v138, s[38:39]
	s_waitcnt vmcnt(8)
	s_waitcnt lgkmcnt(0)
	s_barrier
	s_waitcnt lgkmcnt(0)
	v_mfma_f32_16x16x32_bf16 v[124:127], v[144:147], v[184:187], v[124:127]
	v_mfma_f32_16x16x32_bf16 v[120:123], v[160:163], v[184:187], v[120:123]
	v_mfma_f32_16x16x32_bf16 v[108:111], v[144:147], v[192:195], v[108:111]
	v_mfma_f32_16x16x32_bf16 v[104:107], v[160:163], v[192:195], v[104:107]
	v_mfma_f32_16x16x32_bf16 v[92:95], v[144:147], v[200:203], v[92:95]
	v_mfma_f32_16x16x32_bf16 v[88:91], v[160:163], v[200:203], v[88:91]
	v_mfma_f32_16x16x32_bf16 v[76:79], v[144:147], v[208:211], v[76:79]
	v_mfma_f32_16x16x32_bf16 v[72:75], v[160:163], v[208:211], v[72:75]
	v_mfma_f32_16x16x32_bf16 v[124:127], v[156:159], v[188:191], v[124:127]
	v_mfma_f32_16x16x32_bf16 v[120:123], v[164:167], v[188:191], v[120:123]
	v_mfma_f32_16x16x32_bf16 v[108:111], v[156:159], v[196:199], v[108:111]
	v_mfma_f32_16x16x32_bf16 v[104:107], v[164:167], v[196:199], v[104:107]
	v_mfma_f32_16x16x32_bf16 v[92:95], v[156:159], v[204:207], v[92:95]
	v_mfma_f32_16x16x32_bf16 v[88:91], v[164:167], v[204:207], v[88:91]
	v_mfma_f32_16x16x32_bf16 v[76:79], v[156:159], v[212:215], v[76:79]
	v_mfma_f32_16x16x32_bf16 v[72:75], v[164:167], v[212:215], v[72:75]
	v_mfma_f32_16x16x32_bf16 v[116:119], v[168:171], v[184:187], v[116:119]
	v_mfma_f32_16x16x32_bf16 v[112:115], v[176:179], v[184:187], v[112:115]
	v_mfma_f32_16x16x32_bf16 v[100:103], v[168:171], v[192:195], v[100:103]
	v_mfma_f32_16x16x32_bf16 v[96:99], v[176:179], v[192:195], v[96:99]
	v_mfma_f32_16x16x32_bf16 v[84:87], v[168:171], v[200:203], v[84:87]
	v_mfma_f32_16x16x32_bf16 v[80:83], v[176:179], v[200:203], v[80:83]
	v_mfma_f32_16x16x32_bf16 v[68:71], v[168:171], v[208:211], v[68:71]
	v_mfma_f32_16x16x32_bf16 v[64:67], v[176:179], v[208:211], v[64:67]
	v_mfma_f32_16x16x32_bf16 v[116:119], v[172:175], v[188:191], v[116:119]
	v_mfma_f32_16x16x32_bf16 v[112:115], v[180:183], v[188:191], v[112:115]
	v_mfma_f32_16x16x32_bf16 v[100:103], v[172:175], v[196:199], v[100:103]
	v_mfma_f32_16x16x32_bf16 v[96:99], v[180:183], v[196:199], v[96:99]
	v_mfma_f32_16x16x32_bf16 v[84:87], v[172:175], v[204:207], v[84:87]
	v_mfma_f32_16x16x32_bf16 v[80:83], v[180:183], v[204:207], v[80:83]
	v_mfma_f32_16x16x32_bf16 v[68:71], v[172:175], v[212:215], v[68:71]
	v_mfma_f32_16x16x32_bf16 v[64:67], v[180:183], v[212:215], v[64:67]
	s_barrier
	s_add_i32 s37, s61, s67
	s_mov_b32 m0, s37
	ds_read_b128 v[184:187], v155 offset:16384
	ds_read_b128 v[188:191], v155 offset:17408
	ds_read_b128 v[192:195], v155 offset:18432
	ds_read_b128 v[196:199], v155 offset:19456
	ds_read_b128 v[200:203], v155 offset:20480
	ds_read_b128 v[204:207], v155 offset:21504
	ds_read_b128 v[208:211], v155 offset:22528
	ds_read_b128 v[212:215], v155 offset:23552
	global_load_lds_dwordx4 v130, s[46:47]
	s_add_i32 m0, s37, 0x2000
	s_add_u32 s40, s46, 0x100000
	s_addc_u32 s41, s47, 0
	s_add_i32 s37, s62, s67
	global_load_lds_dwordx4 v134, s[46:47]
	s_mov_b32 m0, s37
	global_load_lds_dwordx4 v130, s[40:41]
	s_add_i32 m0, s37, 0x2000
	s_nop 0
	global_load_lds_dwordx4 v134, s[40:41]
	s_mov_b32 m0, s76
	s_nop 0
	global_load_lds_dwordx4 v128, s[48:49]
	s_mov_b32 m0, s52
	s_nop 0
	global_load_lds_dwordx4 v132, s[48:49]
	s_waitcnt vmcnt(8)
	s_waitcnt lgkmcnt(0)
	s_barrier
	s_waitcnt lgkmcnt(0)
	v_mfma_f32_16x16x32_bf16 v[60:63], v[144:147], v[184:187], v[60:63]
	v_mfma_f32_16x16x32_bf16 v[56:59], v[160:163], v[184:187], v[56:59]
	v_mfma_f32_16x16x32_bf16 v[44:47], v[144:147], v[192:195], v[44:47]
	v_mfma_f32_16x16x32_bf16 v[40:43], v[160:163], v[192:195], v[40:43]
	v_mfma_f32_16x16x32_bf16 v[28:31], v[144:147], v[200:203], v[28:31]
	v_mfma_f32_16x16x32_bf16 v[24:27], v[160:163], v[200:203], v[24:27]
	v_mfma_f32_16x16x32_bf16 v[12:15], v[144:147], v[208:211], v[12:15]
	v_mfma_f32_16x16x32_bf16 v[8:11], v[160:163], v[208:211], v[8:11]
	v_mfma_f32_16x16x32_bf16 v[60:63], v[156:159], v[188:191], v[60:63]
	v_mfma_f32_16x16x32_bf16 v[56:59], v[164:167], v[188:191], v[56:59]
	v_mfma_f32_16x16x32_bf16 v[44:47], v[156:159], v[196:199], v[44:47]
	v_mfma_f32_16x16x32_bf16 v[40:43], v[164:167], v[196:199], v[40:43]
	v_mfma_f32_16x16x32_bf16 v[28:31], v[156:159], v[204:207], v[28:31]
	v_mfma_f32_16x16x32_bf16 v[24:27], v[164:167], v[204:207], v[24:27]
	v_mfma_f32_16x16x32_bf16 v[12:15], v[156:159], v[212:215], v[12:15]
	v_mfma_f32_16x16x32_bf16 v[8:11], v[164:167], v[212:215], v[8:11]
	v_mfma_f32_16x16x32_bf16 v[52:55], v[168:171], v[184:187], v[52:55]
	v_mfma_f32_16x16x32_bf16 v[48:51], v[176:179], v[184:187], v[48:51]
	v_mfma_f32_16x16x32_bf16 v[36:39], v[168:171], v[192:195], v[36:39]
	v_mfma_f32_16x16x32_bf16 v[32:35], v[176:179], v[192:195], v[32:35]
	v_mfma_f32_16x16x32_bf16 v[20:23], v[168:171], v[200:203], v[20:23]
	v_mfma_f32_16x16x32_bf16 v[16:19], v[176:179], v[200:203], v[16:19]
	v_mfma_f32_16x16x32_bf16 v[4:7], v[168:171], v[208:211], v[4:7]
	v_mfma_f32_16x16x32_bf16 v[0:3], v[176:179], v[208:211], v[0:3]
	v_mfma_f32_16x16x32_bf16 v[52:55], v[172:175], v[188:191], v[52:55]
	v_mfma_f32_16x16x32_bf16 v[48:51], v[180:183], v[188:191], v[48:51]
	v_mfma_f32_16x16x32_bf16 v[36:39], v[172:175], v[196:199], v[36:39]
	v_mfma_f32_16x16x32_bf16 v[32:35], v[180:183], v[196:199], v[32:35]
	v_mfma_f32_16x16x32_bf16 v[20:23], v[172:175], v[204:207], v[20:23]
	v_mfma_f32_16x16x32_bf16 v[16:19], v[180:183], v[204:207], v[16:19]
	v_mfma_f32_16x16x32_bf16 v[4:7], v[172:175], v[212:215], v[4:7]
	v_mfma_f32_16x16x32_bf16 v[0:3], v[180:183], v[212:215], v[0:3]
	s_barrier
	s_add_i32 s37, 0, 0x18000
	s_add_i32 s42, 0, 0x1c000
	v_add_u32_e32 v164, s37, v151
	v_add_u32_e32 v180, s42, v151
	ds_read_b128 v[144:147], v164
	ds_read_b128 v[156:159], v164 offset:1024
	ds_read_b128 v[160:163], v164 offset:2048
	ds_read_b128 v[164:167], v164 offset:3072
	ds_read_b128 v[168:171], v180
	ds_read_b128 v[172:175], v180 offset:1024
	ds_read_b128 v[176:179], v180 offset:2048
	ds_read_b128 v[180:183], v180 offset:3072
	s_add_u32 s40, s48, 0x100000
	s_addc_u32 s41, s49, 0
	s_mov_b32 m0, s53
	ds_read_b128 v[184:187], v155 offset:32768
	ds_read_b128 v[188:191], v155 offset:33792
	ds_read_b128 v[192:195], v155 offset:34816
	ds_read_b128 v[196:199], v155 offset:35840
	ds_read_b128 v[200:203], v155 offset:36864
	ds_read_b128 v[204:207], v155 offset:37888
	ds_read_b128 v[208:211], v155 offset:38912
	ds_read_b128 v[212:215], v155 offset:39936
	global_load_lds_dwordx4 v128, s[40:41]
	s_mov_b32 m0, s54
	s_nop 0
	global_load_lds_dwordx4 v132, s[40:41]
	s_waitcnt vmcnt(8)
	s_waitcnt lgkmcnt(0)
	s_barrier
	s_waitcnt lgkmcnt(0)
	v_mfma_f32_16x16x32_bf16 v[124:127], v[144:147], v[184:187], v[124:127]
	v_mfma_f32_16x16x32_bf16 v[120:123], v[160:163], v[184:187], v[120:123]
	v_mfma_f32_16x16x32_bf16 v[108:111], v[144:147], v[192:195], v[108:111]
	v_mfma_f32_16x16x32_bf16 v[104:107], v[160:163], v[192:195], v[104:107]
	v_mfma_f32_16x16x32_bf16 v[92:95], v[144:147], v[200:203], v[92:95]
	v_mfma_f32_16x16x32_bf16 v[88:91], v[160:163], v[200:203], v[88:91]
	v_mfma_f32_16x16x32_bf16 v[76:79], v[144:147], v[208:211], v[76:79]
	v_mfma_f32_16x16x32_bf16 v[72:75], v[160:163], v[208:211], v[72:75]
	v_mfma_f32_16x16x32_bf16 v[124:127], v[156:159], v[188:191], v[124:127]
	v_mfma_f32_16x16x32_bf16 v[120:123], v[164:167], v[188:191], v[120:123]
	v_mfma_f32_16x16x32_bf16 v[108:111], v[156:159], v[196:199], v[108:111]
	v_mfma_f32_16x16x32_bf16 v[104:107], v[164:167], v[196:199], v[104:107]
	v_mfma_f32_16x16x32_bf16 v[92:95], v[156:159], v[204:207], v[92:95]
	v_mfma_f32_16x16x32_bf16 v[88:91], v[164:167], v[204:207], v[88:91]
	v_mfma_f32_16x16x32_bf16 v[76:79], v[156:159], v[212:215], v[76:79]
	v_mfma_f32_16x16x32_bf16 v[72:75], v[164:167], v[212:215], v[72:75]
	v_mfma_f32_16x16x32_bf16 v[116:119], v[168:171], v[184:187], v[116:119]
	v_mfma_f32_16x16x32_bf16 v[112:115], v[176:179], v[184:187], v[112:115]
	v_mfma_f32_16x16x32_bf16 v[100:103], v[168:171], v[192:195], v[100:103]
	v_mfma_f32_16x16x32_bf16 v[96:99], v[176:179], v[192:195], v[96:99]
	v_mfma_f32_16x16x32_bf16 v[84:87], v[168:171], v[200:203], v[84:87]
	v_mfma_f32_16x16x32_bf16 v[80:83], v[176:179], v[200:203], v[80:83]
	v_mfma_f32_16x16x32_bf16 v[68:71], v[168:171], v[208:211], v[68:71]
	v_mfma_f32_16x16x32_bf16 v[64:67], v[176:179], v[208:211], v[64:67]
	v_mfma_f32_16x16x32_bf16 v[116:119], v[172:175], v[188:191], v[116:119]
	v_mfma_f32_16x16x32_bf16 v[112:115], v[180:183], v[188:191], v[112:115]
	v_mfma_f32_16x16x32_bf16 v[100:103], v[172:175], v[196:199], v[100:103]
	v_mfma_f32_16x16x32_bf16 v[96:99], v[180:183], v[196:199], v[96:99]
	v_mfma_f32_16x16x32_bf16 v[84:87], v[172:175], v[204:207], v[84:87]
	v_mfma_f32_16x16x32_bf16 v[80:83], v[180:183], v[204:207], v[80:83]
	v_mfma_f32_16x16x32_bf16 v[68:71], v[172:175], v[212:215], v[68:71]
	v_mfma_f32_16x16x32_bf16 v[64:67], v[180:183], v[212:215], v[64:67]
	s_barrier
	s_add_i32 s37, s37, s67
	s_mov_b32 m0, s37
	ds_read_b128 v[184:187], v155 offset:49152
	ds_read_b128 v[188:191], v155 offset:50176
	ds_read_b128 v[192:195], v155 offset:51200
	ds_read_b128 v[196:199], v155 offset:52224
	ds_read_b128 v[200:203], v155 offset:53248
	ds_read_b128 v[204:207], v155 offset:54272
	ds_read_b128 v[208:211], v155 offset:55296
	ds_read_b128 v[212:215], v155 offset:56320
	s_add_u32 s100, s46, 0x80
	s_addc_u32 s101, s47, 0
	global_load_lds_dwordx4 v130, s[100:101]
	s_add_i32 m0, s37, 0x2000
	s_add_u32 s40, s46, 0x100080
	s_addc_u32 s41, s47, 0
	s_add_i32 s37, s42, s67
	s_add_u32 s100, s46, 0x80
	s_addc_u32 s101, s47, 0
	global_load_lds_dwordx4 v134, s[100:101]
	s_mov_b32 m0, s37
	s_nop 0
	global_load_lds_dwordx4 v130, s[40:41]
	s_add_i32 m0, s37, 0x2000
	s_nop 0
	global_load_lds_dwordx4 v134, s[40:41]
	s_mov_b32 m0, s56
	s_nop 0
	s_add_u32 s100, s48, 0x80
	s_addc_u32 s101, s49, 0
	global_load_lds_dwordx4 v128, s[100:101]
	s_mov_b32 m0, s57
	s_nop 0
	s_add_u32 s100, s48, 0x80
	s_addc_u32 s101, s49, 0
	global_load_lds_dwordx4 v132, s[100:101]
	s_waitcnt vmcnt(8)
	s_waitcnt lgkmcnt(0)
	s_barrier
	s_waitcnt lgkmcnt(0)
	v_mfma_f32_16x16x32_bf16 v[60:63], v[144:147], v[184:187], v[60:63]
	v_mfma_f32_16x16x32_bf16 v[56:59], v[160:163], v[184:187], v[56:59]
	v_mfma_f32_16x16x32_bf16 v[44:47], v[144:147], v[192:195], v[44:47]
	v_mfma_f32_16x16x32_bf16 v[40:43], v[160:163], v[192:195], v[40:43]
	v_mfma_f32_16x16x32_bf16 v[28:31], v[144:147], v[200:203], v[28:31]
	v_mfma_f32_16x16x32_bf16 v[24:27], v[160:163], v[200:203], v[24:27]
	v_mfma_f32_16x16x32_bf16 v[12:15], v[144:147], v[208:211], v[12:15]
	v_mfma_f32_16x16x32_bf16 v[8:11], v[160:163], v[208:211], v[8:11]
	v_mfma_f32_16x16x32_bf16 v[60:63], v[156:159], v[188:191], v[60:63]
	v_mfma_f32_16x16x32_bf16 v[56:59], v[164:167], v[188:191], v[56:59]
	v_mfma_f32_16x16x32_bf16 v[44:47], v[156:159], v[196:199], v[44:47]
	v_mfma_f32_16x16x32_bf16 v[40:43], v[164:167], v[196:199], v[40:43]
	v_mfma_f32_16x16x32_bf16 v[28:31], v[156:159], v[204:207], v[28:31]
	v_mfma_f32_16x16x32_bf16 v[24:27], v[164:167], v[204:207], v[24:27]
	v_mfma_f32_16x16x32_bf16 v[12:15], v[156:159], v[212:215], v[12:15]
	v_mfma_f32_16x16x32_bf16 v[8:11], v[164:167], v[212:215], v[8:11]
	v_mfma_f32_16x16x32_bf16 v[52:55], v[168:171], v[184:187], v[52:55]
	v_mfma_f32_16x16x32_bf16 v[48:51], v[176:179], v[184:187], v[48:51]
	v_mfma_f32_16x16x32_bf16 v[36:39], v[168:171], v[192:195], v[36:39]
	v_mfma_f32_16x16x32_bf16 v[32:35], v[176:179], v[192:195], v[32:35]
	v_mfma_f32_16x16x32_bf16 v[20:23], v[168:171], v[200:203], v[20:23]
	v_mfma_f32_16x16x32_bf16 v[16:19], v[176:179], v[200:203], v[16:19]
	v_mfma_f32_16x16x32_bf16 v[4:7], v[168:171], v[208:211], v[4:7]
	v_mfma_f32_16x16x32_bf16 v[0:3], v[176:179], v[208:211], v[0:3]
	v_mfma_f32_16x16x32_bf16 v[52:55], v[172:175], v[188:191], v[52:55]
	v_mfma_f32_16x16x32_bf16 v[48:51], v[180:183], v[188:191], v[48:51]
	v_mfma_f32_16x16x32_bf16 v[36:39], v[172:175], v[196:199], v[36:39]
	v_mfma_f32_16x16x32_bf16 v[32:35], v[180:183], v[196:199], v[32:35]
	v_mfma_f32_16x16x32_bf16 v[20:23], v[172:175], v[204:207], v[20:23]
	v_mfma_f32_16x16x32_bf16 v[16:19], v[180:183], v[204:207], v[16:19]
	v_mfma_f32_16x16x32_bf16 v[4:7], v[172:175], v[212:215], v[4:7]
	v_mfma_f32_16x16x32_bf16 v[0:3], v[180:183], v[212:215], v[0:3]
	s_barrier
	s_add_i32 s36, s36, 2
	s_add_u32 s38, s38, 0x100
	s_addc_u32 s39, s39, 0
	s_add_u32 s34, s34, 0x100
	s_addc_u32 s35, s35, 0
	s_cmp_gt_u32 s36, 61
	s_cbranch_scc0 .LBB0_758
	s_setprio 0
	s_and_b64 vcc, exec, s[8:9]
	s_cbranch_vccz .LBB0_761
	s_barrier

.Lmy_prio_skip5:
.LBB0_914:
	ds_read_b128 v[128:131], v187
	ds_read_b128 v[132:135], v187 offset:1024
	ds_read_b128 v[136:139], v187 offset:2048
	ds_read_b128 v[140:143], v187 offset:3072
	ds_read_b128 v[144:147], v188
	ds_read_b128 v[148:151], v188 offset:1024
	ds_read_b128 v[152:155], v188 offset:2048
	ds_read_b128 v[156:159], v188 offset:3072
	s_add_u32 s52, s50, 0x100
	s_addc_u32 s53, s51, 0
	s_cmp_eq_u32 s96, 60
	s_cselect_b32 s57, s41, s53
	s_cselect_b32 s56, s47, s52
	s_cselect_b32 s55, s39, s49
	s_cselect_b32 s54, s34, s35
	s_add_i32 m0, s67, 0xc000
	ds_read_b128 v[178:181], v189
	ds_read_b128 v[192:195], v189 offset:1024
	ds_read_b128 v[196:199], v189 offset:2048
	ds_read_b128 v[200:203], v189 offset:3072
	ds_read_b128 v[204:207], v189 offset:4096
	ds_read_b128 v[208:211], v189 offset:5120
	ds_read_b128 v[212:215], v189 offset:6144
	ds_read_b128 v[216:219], v189 offset:7168
	global_load_lds_dwordx4 v170, s[50:51]
	s_add_i32 m0, s67, 0xe000
	s_nop 0
	global_load_lds_dwordx4 v172, s[50:51]
	s_waitcnt vmcnt(8)
	s_waitcnt lgkmcnt(0)
	s_barrier
	s_waitcnt lgkmcnt(0)
	v_mfma_f32_16x16x32_bf16 v[124:127], v[128:131], v[178:181], v[124:127]
	v_mfma_f32_16x16x32_bf16 v[60:63], v[136:139], v[178:181], v[60:63]
	v_mfma_f32_16x16x32_bf16 v[116:119], v[128:131], v[196:199], v[116:119]
	v_mfma_f32_16x16x32_bf16 v[56:59], v[136:139], v[196:199], v[56:59]
	v_mfma_f32_16x16x32_bf16 v[108:111], v[128:131], v[204:207], v[108:111]
	v_mfma_f32_16x16x32_bf16 v[44:47], v[136:139], v[204:207], v[44:47]
	v_mfma_f32_16x16x32_bf16 v[104:107], v[128:131], v[212:215], v[104:107]
	v_mfma_f32_16x16x32_bf16 v[40:43], v[136:139], v[212:215], v[40:43]
	v_mfma_f32_16x16x32_bf16 v[124:127], v[132:135], v[192:195], v[124:127]
	v_mfma_f32_16x16x32_bf16 v[60:63], v[140:143], v[192:195], v[60:63]
	v_mfma_f32_16x16x32_bf16 v[116:119], v[132:135], v[200:203], v[116:119]
	v_mfma_f32_16x16x32_bf16 v[56:59], v[140:143], v[200:203], v[56:59]
	v_mfma_f32_16x16x32_bf16 v[108:111], v[132:135], v[208:211], v[108:111]
	v_mfma_f32_16x16x32_bf16 v[44:47], v[140:143], v[208:211], v[44:47]
	v_mfma_f32_16x16x32_bf16 v[104:107], v[132:135], v[216:219], v[104:107]
	v_mfma_f32_16x16x32_bf16 v[40:43], v[140:143], v[216:219], v[40:43]
	v_mfma_f32_16x16x32_bf16 v[120:123], v[144:147], v[178:181], v[120:123]
	v_mfma_f32_16x16x32_bf16 v[52:55], v[152:155], v[178:181], v[52:55]
	v_mfma_f32_16x16x32_bf16 v[112:115], v[144:147], v[196:199], v[112:115]
	v_mfma_f32_16x16x32_bf16 v[48:51], v[152:155], v[196:199], v[48:51]
	v_mfma_f32_16x16x32_bf16 v[100:103], v[144:147], v[204:207], v[100:103]
	v_mfma_f32_16x16x32_bf16 v[36:39], v[152:155], v[204:207], v[36:39]
	v_mfma_f32_16x16x32_bf16 v[96:99], v[144:147], v[212:215], v[96:99]
	v_mfma_f32_16x16x32_bf16 v[32:35], v[152:155], v[212:215], v[32:35]
	v_mfma_f32_16x16x32_bf16 v[120:123], v[148:151], v[192:195], v[120:123]
	v_mfma_f32_16x16x32_bf16 v[52:55], v[156:159], v[192:195], v[52:55]
	v_mfma_f32_16x16x32_bf16 v[112:115], v[148:151], v[200:203], v[112:115]
	v_mfma_f32_16x16x32_bf16 v[48:51], v[156:159], v[200:203], v[48:51]
	v_mfma_f32_16x16x32_bf16 v[100:103], v[148:151], v[208:211], v[100:103]
	v_mfma_f32_16x16x32_bf16 v[36:39], v[156:159], v[208:211], v[36:39]
	v_mfma_f32_16x16x32_bf16 v[96:99], v[148:151], v[216:219], v[96:99]
	v_mfma_f32_16x16x32_bf16 v[32:35], v[156:159], v[216:219], v[32:35]
	s_barrier
	s_add_i32 s50, s92, s66
	s_mov_b32 m0, s50
	ds_read_b128 v[178:181], v189 offset:16384
	ds_read_b128 v[192:195], v189 offset:17408
	ds_read_b128 v[196:199], v189 offset:18432
	ds_read_b128 v[200:203], v189 offset:19456
	ds_read_b128 v[204:207], v189 offset:20480
	ds_read_b128 v[208:211], v189 offset:21504
	ds_read_b128 v[212:215], v189 offset:22528
	ds_read_b128 v[216:219], v189 offset:23552
	global_load_lds_dwordx4 v164, s[54:55]
	s_add_i32 m0, s50, 0x2000
	s_add_u32 s50, s54, 0x100000
	v_lshl_add_u64 v[182:183], s[54:55], 0, v[168:169]
	s_addc_u32 s51, s55, 0
	s_add_i32 s97, s93, s66
	global_load_lds_dwordx4 v168, s[54:55]
	s_mov_b32 m0, s97
	global_load_lds_dwordx4 v164, s[50:51]
	s_add_i32 m0, s97, 0x2000
	s_nop 0
	global_load_lds_dwordx4 v168, s[50:51]
	s_mov_b32 m0, s67
	s_nop 0
	global_load_lds_dwordx4 v162, s[56:57]
	s_mov_b32 m0, s68
	s_nop 0
	global_load_lds_dwordx4 v166, s[56:57]
	s_waitcnt vmcnt(8)
	s_waitcnt lgkmcnt(0)
	s_barrier
	s_waitcnt lgkmcnt(0)
	v_mfma_f32_16x16x32_bf16 v[92:95], v[128:131], v[178:181], v[92:95]
	v_mfma_f32_16x16x32_bf16 v[28:31], v[136:139], v[178:181], v[28:31]
	v_mfma_f32_16x16x32_bf16 v[84:87], v[128:131], v[196:199], v[84:87]
	v_mfma_f32_16x16x32_bf16 v[24:27], v[136:139], v[196:199], v[24:27]
	v_mfma_f32_16x16x32_bf16 v[76:79], v[128:131], v[204:207], v[76:79]
	v_mfma_f32_16x16x32_bf16 v[12:15], v[136:139], v[204:207], v[12:15]
	v_mfma_f32_16x16x32_bf16 v[72:75], v[128:131], v[212:215], v[72:75]
	v_mfma_f32_16x16x32_bf16 v[8:11], v[136:139], v[212:215], v[8:11]
	v_mfma_f32_16x16x32_bf16 v[92:95], v[132:135], v[192:195], v[92:95]
	v_mfma_f32_16x16x32_bf16 v[28:31], v[140:143], v[192:195], v[28:31]
	v_mfma_f32_16x16x32_bf16 v[84:87], v[132:135], v[200:203], v[84:87]
	v_mfma_f32_16x16x32_bf16 v[24:27], v[140:143], v[200:203], v[24:27]
	v_mfma_f32_16x16x32_bf16 v[76:79], v[132:135], v[208:211], v[76:79]
	v_mfma_f32_16x16x32_bf16 v[12:15], v[140:143], v[208:211], v[12:15]
	v_mfma_f32_16x16x32_bf16 v[72:75], v[132:135], v[216:219], v[72:75]
	v_mfma_f32_16x16x32_bf16 v[8:11], v[140:143], v[216:219], v[8:11]
	v_mfma_f32_16x16x32_bf16 v[88:91], v[144:147], v[178:181], v[88:91]
	v_mfma_f32_16x16x32_bf16 v[20:23], v[152:155], v[178:181], v[20:23]
	v_mfma_f32_16x16x32_bf16 v[80:83], v[144:147], v[196:199], v[80:83]
	v_mfma_f32_16x16x32_bf16 v[16:19], v[152:155], v[196:199], v[16:19]
	v_mfma_f32_16x16x32_bf16 v[68:71], v[144:147], v[204:207], v[68:71]
	v_mfma_f32_16x16x32_bf16 v[4:7], v[152:155], v[204:207], v[4:7]
	v_mfma_f32_16x16x32_bf16 v[64:67], v[144:147], v[212:215], v[64:67]
	v_mfma_f32_16x16x32_bf16 v[0:3], v[152:155], v[212:215], v[0:3]
	v_mfma_f32_16x16x32_bf16 v[88:91], v[148:151], v[192:195], v[88:91]
	v_mfma_f32_16x16x32_bf16 v[20:23], v[156:159], v[192:195], v[20:23]
	v_mfma_f32_16x16x32_bf16 v[80:83], v[148:151], v[200:203], v[80:83]
	v_mfma_f32_16x16x32_bf16 v[16:19], v[156:159], v[200:203], v[16:19]
	v_mfma_f32_16x16x32_bf16 v[68:71], v[148:151], v[208:211], v[68:71]
	v_mfma_f32_16x16x32_bf16 v[4:7], v[156:159], v[208:211], v[4:7]
	v_mfma_f32_16x16x32_bf16 v[64:67], v[148:151], v[216:219], v[64:67]
	v_mfma_f32_16x16x32_bf16 v[0:3], v[156:159], v[216:219], v[0:3]
	s_barrier
	s_add_i32 s97, 0, 0x18000
	s_add_i32 vcc_lo, 0, 0x1c000
	v_add_u32_e32 v140, s97, v184
	v_add_u32_e32 v156, vcc_lo, v184
	ds_read_b128 v[128:131], v140
	ds_read_b128 v[132:135], v140 offset:1024
	ds_read_b128 v[136:139], v140 offset:2048
	ds_read_b128 v[140:143], v140 offset:3072
	ds_read_b128 v[144:147], v156
	ds_read_b128 v[148:151], v156 offset:1024
	ds_read_b128 v[152:155], v156 offset:2048
	ds_read_b128 v[156:159], v156 offset:3072
	s_add_u32 s50, s56, 0x100000
	s_addc_u32 s51, s57, 0
	s_mov_b32 m0, s69
	ds_read_b128 v[178:181], v189 offset:32768
	ds_read_b128 v[192:195], v189 offset:33792
	ds_read_b128 v[196:199], v189 offset:34816
	ds_read_b128 v[200:203], v189 offset:35840
	ds_read_b128 v[204:207], v189 offset:36864
	ds_read_b128 v[208:211], v189 offset:37888
	ds_read_b128 v[212:215], v189 offset:38912
	ds_read_b128 v[216:219], v189 offset:39936
	global_load_lds_dwordx4 v162, s[50:51]
	s_mov_b32 m0, s76
	s_nop 0
	global_load_lds_dwordx4 v166, s[50:51]
	s_waitcnt vmcnt(8)
	s_waitcnt lgkmcnt(0)
	s_barrier
	s_waitcnt lgkmcnt(0)
	v_mfma_f32_16x16x32_bf16 v[124:127], v[128:131], v[178:181], v[124:127]
	v_mfma_f32_16x16x32_bf16 v[60:63], v[136:139], v[178:181], v[60:63]
	v_mfma_f32_16x16x32_bf16 v[116:119], v[128:131], v[196:199], v[116:119]
	v_mfma_f32_16x16x32_bf16 v[56:59], v[136:139], v[196:199], v[56:59]
	v_mfma_f32_16x16x32_bf16 v[108:111], v[128:131], v[204:207], v[108:111]
	v_mfma_f32_16x16x32_bf16 v[44:47], v[136:139], v[204:207], v[44:47]
	v_mfma_f32_16x16x32_bf16 v[104:107], v[128:131], v[212:215], v[104:107]
	v_mfma_f32_16x16x32_bf16 v[40:43], v[136:139], v[212:215], v[40:43]
	v_mfma_f32_16x16x32_bf16 v[124:127], v[132:135], v[192:195], v[124:127]
	v_mfma_f32_16x16x32_bf16 v[60:63], v[140:143], v[192:195], v[60:63]
	v_mfma_f32_16x16x32_bf16 v[116:119], v[132:135], v[200:203], v[116:119]
	v_mfma_f32_16x16x32_bf16 v[56:59], v[140:143], v[200:203], v[56:59]
	v_mfma_f32_16x16x32_bf16 v[108:111], v[132:135], v[208:211], v[108:111]
	v_mfma_f32_16x16x32_bf16 v[44:47], v[140:143], v[208:211], v[44:47]
	v_mfma_f32_16x16x32_bf16 v[104:107], v[132:135], v[216:219], v[104:107]
	v_mfma_f32_16x16x32_bf16 v[40:43], v[140:143], v[216:219], v[40:43]
	v_mfma_f32_16x16x32_bf16 v[120:123], v[144:147], v[178:181], v[120:123]
	v_mfma_f32_16x16x32_bf16 v[52:55], v[152:155], v[178:181], v[52:55]
	v_mfma_f32_16x16x32_bf16 v[112:115], v[144:147], v[196:199], v[112:115]
	v_mfma_f32_16x16x32_bf16 v[48:51], v[152:155], v[196:199], v[48:51]
	v_mfma_f32_16x16x32_bf16 v[100:103], v[144:147], v[204:207], v[100:103]
	v_mfma_f32_16x16x32_bf16 v[36:39], v[152:155], v[204:207], v[36:39]
	v_mfma_f32_16x16x32_bf16 v[96:99], v[144:147], v[212:215], v[96:99]
	v_mfma_f32_16x16x32_bf16 v[32:35], v[152:155], v[212:215], v[32:35]
	v_mfma_f32_16x16x32_bf16 v[120:123], v[148:151], v[192:195], v[120:123]
	v_mfma_f32_16x16x32_bf16 v[52:55], v[156:159], v[192:195], v[52:55]
	v_mfma_f32_16x16x32_bf16 v[112:115], v[148:151], v[200:203], v[112:115]
	v_mfma_f32_16x16x32_bf16 v[48:51], v[156:159], v[200:203], v[48:51]
	v_mfma_f32_16x16x32_bf16 v[100:103], v[148:151], v[208:211], v[100:103]
	v_mfma_f32_16x16x32_bf16 v[36:39], v[156:159], v[208:211], v[36:39]
	v_mfma_f32_16x16x32_bf16 v[96:99], v[148:151], v[216:219], v[96:99]
	v_mfma_f32_16x16x32_bf16 v[32:35], v[156:159], v[216:219], v[32:35]
	s_barrier
	s_add_i32 s50, s97, s66
	s_mov_b32 m0, s50
	ds_read_b128 v[178:181], v189 offset:49152
	ds_read_b128 v[192:195], v189 offset:50176
	ds_read_b128 v[196:199], v189 offset:51200
	ds_read_b128 v[200:203], v189 offset:52224
	ds_read_b128 v[204:207], v189 offset:53248
	ds_read_b128 v[208:211], v189 offset:54272
	ds_read_b128 v[212:215], v189 offset:55296
	ds_read_b128 v[216:219], v189 offset:56320
	s_add_u32 s100, s54, 0x80
	s_addc_u32 s101, s55, 0
	global_load_lds_dwordx4 v164, s[100:101]
	s_add_i32 m0, s50, 0x2000
	s_add_u32 s50, s54, 0x100080
	v_lshl_add_u64 v[160:161], v[182:183], 0, s[10:11]
	s_addc_u32 s51, s55, 0
	s_add_i32 s54, vcc_lo, s66
	global_load_lds_dwordx4 v[160:161], off
	s_mov_b32 m0, s54
	s_nop 0
	global_load_lds_dwordx4 v164, s[50:51]
	s_add_i32 m0, s54, 0x2000
	s_nop 0
	global_load_lds_dwordx4 v168, s[50:51]
	s_mov_b32 m0, s84
	s_nop 0
	s_add_u32 s100, s56, 0x80
	s_addc_u32 s101, s57, 0
	global_load_lds_dwordx4 v162, s[100:101]
	s_mov_b32 m0, s85
	s_nop 0
	s_add_u32 s100, s56, 0x80
	s_addc_u32 s101, s57, 0
	global_load_lds_dwordx4 v166, s[100:101]
	s_waitcnt vmcnt(8)
	s_waitcnt lgkmcnt(0)
	s_barrier
	s_waitcnt lgkmcnt(0)
	v_mfma_f32_16x16x32_bf16 v[92:95], v[128:131], v[178:181], v[92:95]
	v_mfma_f32_16x16x32_bf16 v[28:31], v[136:139], v[178:181], v[28:31]
	v_mfma_f32_16x16x32_bf16 v[84:87], v[128:131], v[196:199], v[84:87]
	v_mfma_f32_16x16x32_bf16 v[24:27], v[136:139], v[196:199], v[24:27]
	v_mfma_f32_16x16x32_bf16 v[76:79], v[128:131], v[204:207], v[76:79]
	v_mfma_f32_16x16x32_bf16 v[12:15], v[136:139], v[204:207], v[12:15]
	v_mfma_f32_16x16x32_bf16 v[72:75], v[128:131], v[212:215], v[72:75]
	v_mfma_f32_16x16x32_bf16 v[8:11], v[136:139], v[212:215], v[8:11]
	v_mfma_f32_16x16x32_bf16 v[92:95], v[132:135], v[192:195], v[92:95]
	v_mfma_f32_16x16x32_bf16 v[28:31], v[140:143], v[192:195], v[28:31]
	v_mfma_f32_16x16x32_bf16 v[84:87], v[132:135], v[200:203], v[84:87]
	v_mfma_f32_16x16x32_bf16 v[24:27], v[140:143], v[200:203], v[24:27]
	v_mfma_f32_16x16x32_bf16 v[76:79], v[132:135], v[208:211], v[76:79]
	v_mfma_f32_16x16x32_bf16 v[12:15], v[140:143], v[208:211], v[12:15]
	v_mfma_f32_16x16x32_bf16 v[72:75], v[132:135], v[216:219], v[72:75]
	v_mfma_f32_16x16x32_bf16 v[8:11], v[140:143], v[216:219], v[8:11]
	v_mfma_f32_16x16x32_bf16 v[88:91], v[144:147], v[178:181], v[88:91]
	v_mfma_f32_16x16x32_bf16 v[20:23], v[152:155], v[178:181], v[20:23]
	v_mfma_f32_16x16x32_bf16 v[80:83], v[144:147], v[196:199], v[80:83]
	v_mfma_f32_16x16x32_bf16 v[16:19], v[152:155], v[196:199], v[16:19]
	v_mfma_f32_16x16x32_bf16 v[68:71], v[144:147], v[204:207], v[68:71]
	v_mfma_f32_16x16x32_bf16 v[4:7], v[152:155], v[204:207], v[4:7]
	v_mfma_f32_16x16x32_bf16 v[64:67], v[144:147], v[212:215], v[64:67]
	v_mfma_f32_16x16x32_bf16 v[0:3], v[152:155], v[212:215], v[0:3]
	v_mfma_f32_16x16x32_bf16 v[88:91], v[148:151], v[192:195], v[88:91]
	v_mfma_f32_16x16x32_bf16 v[20:23], v[156:159], v[192:195], v[20:23]
	v_mfma_f32_16x16x32_bf16 v[80:83], v[148:151], v[200:203], v[80:83]
	v_mfma_f32_16x16x32_bf16 v[16:19], v[156:159], v[200:203], v[16:19]
	v_mfma_f32_16x16x32_bf16 v[68:71], v[148:151], v[208:211], v[68:71]
	v_mfma_f32_16x16x32_bf16 v[4:7], v[156:159], v[208:211], v[4:7]
	v_mfma_f32_16x16x32_bf16 v[64:67], v[148:151], v[216:219], v[64:67]
	v_mfma_f32_16x16x32_bf16 v[0:3], v[156:159], v[216:219], v[0:3]
	s_barrier
	s_add_i32 s96, s96, 2
	s_add_u32 s35, s35, 0x100
	s_addc_u32 s49, s49, 0
	s_cmp_gt_u32 s96, 61
	s_mov_b64 s[50:51], s[52:53]
	s_cbranch_scc0 .LBB0_914
	s_setprio 0
	s_lshl_b32 s34, s46, 2
	v_lshl_or_b32 v178, s48, 7, v186
	s_add_i32 s34, s34, s65
	v_ashrrev_i32_e32 v179, 31, v178
	s_mul_hi_i32 s35, s34, 0x30000
	s_mul_i32 s39, s34, 0x30000
	s_and_saveexec_b64 s[48:49], s[0:1]
	s_cbranch_execz .LBB0_917
	s_add_u32 s50, s79, s39
	s_addc_u32 s51, s81, s35
	v_lshl_add_u64 v[132:133], v[178:179], 1, s[50:51]
	v_add_co_u32_e32 v134, vcc, s78, v132
	s_nop 2
	v_cvt_pk_bf16_f32 v128, v124, v125
	s_nop 2
	v_cvt_pk_bf16_f32 v129, v126, v127
	s_nop 2
	v_cvt_pk_bf16_f32 v130, v60, v61
	s_nop 2
	v_cvt_pk_bf16_f32 v131, v62, v63
	s_nop 1
	v_addc_co_u32_e32 v135, vcc, 0, v133, vcc
	s_mov_b32 s17, 0xc000
	global_store_dwordx4 v[132:133], v[128:131], off
	s_nop 1
	s_nop 2
	v_cvt_pk_bf16_f32 v128, v120, v121
	s_nop 2
	v_cvt_pk_bf16_f32 v129, v122, v123
	s_nop 2
	v_cvt_pk_bf16_f32 v130, v52, v53
	s_nop 2
	v_cvt_pk_bf16_f32 v131, v54, v55
	global_store_dwordx4 v[134:135], v[128:131], off
	v_add_co_u32_e32 v134, vcc, s17, v132
	s_nop 0
	s_nop 2
	v_cvt_pk_bf16_f32 v128, v116, v117
	s_nop 2
	v_cvt_pk_bf16_f32 v129, v118, v119
	s_nop 2
	v_cvt_pk_bf16_f32 v130, v56, v57
	s_nop 2
	v_cvt_pk_bf16_f32 v131, v58, v59
	s_nop 0
	v_addc_co_u32_e32 v135, vcc, 0, v133, vcc
	v_add_co_u32_e32 v132, vcc, 0x12000, v132
	global_store_dwordx4 v[134:135], v[128:131], off
	s_nop 0
	v_addc_co_u32_e32 v133, vcc, 0, v133, vcc
	s_nop 2
	v_cvt_pk_bf16_f32 v128, v112, v113
	s_nop 2
	v_cvt_pk_bf16_f32 v129, v114, v115
	s_nop 2
	v_cvt_pk_bf16_f32 v130, v48, v49
	s_nop 2
	v_cvt_pk_bf16_f32 v131, v50, v51
	global_store_dwordx4 v[132:133], v[128:131], off

.Lmy_prio_skip6:
.LBB0_1077:
	ds_read_b128 v[144:147], v153
	ds_read_b128 v[156:159], v153 offset:1024
	ds_read_b128 v[160:163], v153 offset:2048
	ds_read_b128 v[164:167], v153 offset:3072
	ds_read_b128 v[168:171], v154
	ds_read_b128 v[172:175], v154 offset:1024
	ds_read_b128 v[176:179], v154 offset:2048
	ds_read_b128 v[180:183], v154 offset:3072
	s_add_u32 s28, s26, 0x100
	s_addc_u32 s29, s27, 0
	s_cmpk_eq_i32 s53, 0xbc
	s_cselect_b32 s37, s3, s29
	s_cselect_b32 s36, s2, s28
	s_cselect_b32 s31, s25, s35
	s_cselect_b32 s30, s24, s34
	s_add_i32 m0, s39, 0xc000
	ds_read_b128 v[184:187], v155
	ds_read_b128 v[188:191], v155 offset:1024
	ds_read_b128 v[192:195], v155 offset:2048
	ds_read_b128 v[196:199], v155 offset:3072
	ds_read_b128 v[200:203], v155 offset:4096
	ds_read_b128 v[204:207], v155 offset:5120
	ds_read_b128 v[208:211], v155 offset:6144
	ds_read_b128 v[212:215], v155 offset:7168
	global_load_lds_dwordx4 v136, s[26:27]
	s_add_i32 m0, s39, 0xe000
	s_nop 0
	global_load_lds_dwordx4 v138, s[26:27]
	s_waitcnt vmcnt(8)
	s_waitcnt lgkmcnt(0)
	s_barrier
	s_waitcnt lgkmcnt(0)
	v_mfma_f32_16x16x32_bf16 v[124:127], v[144:147], v[184:187], v[124:127]
	v_mfma_f32_16x16x32_bf16 v[120:123], v[160:163], v[184:187], v[120:123]
	v_mfma_f32_16x16x32_bf16 v[108:111], v[144:147], v[192:195], v[108:111]
	v_mfma_f32_16x16x32_bf16 v[104:107], v[160:163], v[192:195], v[104:107]
	v_mfma_f32_16x16x32_bf16 v[92:95], v[144:147], v[200:203], v[92:95]
	v_mfma_f32_16x16x32_bf16 v[88:91], v[160:163], v[200:203], v[88:91]
	v_mfma_f32_16x16x32_bf16 v[76:79], v[144:147], v[208:211], v[76:79]
	v_mfma_f32_16x16x32_bf16 v[72:75], v[160:163], v[208:211], v[72:75]
	v_mfma_f32_16x16x32_bf16 v[124:127], v[156:159], v[188:191], v[124:127]
	v_mfma_f32_16x16x32_bf16 v[120:123], v[164:167], v[188:191], v[120:123]
	v_mfma_f32_16x16x32_bf16 v[108:111], v[156:159], v[196:199], v[108:111]
	v_mfma_f32_16x16x32_bf16 v[104:107], v[164:167], v[196:199], v[104:107]
	v_mfma_f32_16x16x32_bf16 v[92:95], v[156:159], v[204:207], v[92:95]
	v_mfma_f32_16x16x32_bf16 v[88:91], v[164:167], v[204:207], v[88:91]
	v_mfma_f32_16x16x32_bf16 v[76:79], v[156:159], v[212:215], v[76:79]
	v_mfma_f32_16x16x32_bf16 v[72:75], v[164:167], v[212:215], v[72:75]
	v_mfma_f32_16x16x32_bf16 v[116:119], v[168:171], v[184:187], v[116:119]
	v_mfma_f32_16x16x32_bf16 v[112:115], v[176:179], v[184:187], v[112:115]
	v_mfma_f32_16x16x32_bf16 v[100:103], v[168:171], v[192:195], v[100:103]
	v_mfma_f32_16x16x32_bf16 v[96:99], v[176:179], v[192:195], v[96:99]
	v_mfma_f32_16x16x32_bf16 v[84:87], v[168:171], v[200:203], v[84:87]
	v_mfma_f32_16x16x32_bf16 v[80:83], v[176:179], v[200:203], v[80:83]
	v_mfma_f32_16x16x32_bf16 v[68:71], v[168:171], v[208:211], v[68:71]
	v_mfma_f32_16x16x32_bf16 v[64:67], v[176:179], v[208:211], v[64:67]
	v_mfma_f32_16x16x32_bf16 v[116:119], v[172:175], v[188:191], v[116:119]
	v_mfma_f32_16x16x32_bf16 v[112:115], v[180:183], v[188:191], v[112:115]
	v_mfma_f32_16x16x32_bf16 v[100:103], v[172:175], v[196:199], v[100:103]
	v_mfma_f32_16x16x32_bf16 v[96:99], v[180:183], v[196:199], v[96:99]
	v_mfma_f32_16x16x32_bf16 v[84:87], v[172:175], v[204:207], v[84:87]
	v_mfma_f32_16x16x32_bf16 v[80:83], v[180:183], v[204:207], v[80:83]
	v_mfma_f32_16x16x32_bf16 v[68:71], v[172:175], v[212:215], v[68:71]
	v_mfma_f32_16x16x32_bf16 v[64:67], v[180:183], v[212:215], v[64:67]
	s_barrier
	s_add_i32 s26, s47, s38
	s_mov_b32 m0, s26
	ds_read_b128 v[184:187], v155 offset:16384
	ds_read_b128 v[188:191], v155 offset:17408
	ds_read_b128 v[192:195], v155 offset:18432
	ds_read_b128 v[196:199], v155 offset:19456
	ds_read_b128 v[200:203], v155 offset:20480
	ds_read_b128 v[204:207], v155 offset:21504
	ds_read_b128 v[208:211], v155 offset:22528
	ds_read_b128 v[212:215], v155 offset:23552
	global_load_lds_dwordx4 v130, s[30:31]
	s_add_i32 m0, s26, 0x2000
	s_add_u32 s26, s30, 0x300000
	v_lshl_add_u64 v[216:217], s[30:31], 0, v[134:135]
	s_addc_u32 s27, s31, 0
	s_add_i32 s54, s48, s38
	global_load_lds_dwordx4 v134, s[30:31]
	s_mov_b32 m0, s54
	global_load_lds_dwordx4 v130, s[26:27]
	s_add_i32 m0, s54, 0x2000
	s_nop 0
	global_load_lds_dwordx4 v134, s[26:27]
	s_mov_b32 m0, s39
	s_nop 0
	global_load_lds_dwordx4 v128, s[36:37]
	s_mov_b32 m0, s40
	s_nop 0
	global_load_lds_dwordx4 v132, s[36:37]
	s_waitcnt vmcnt(8)
	s_waitcnt lgkmcnt(0)
	s_barrier
	s_waitcnt lgkmcnt(0)
	v_mfma_f32_16x16x32_bf16 v[60:63], v[144:147], v[184:187], v[60:63]
	v_mfma_f32_16x16x32_bf16 v[56:59], v[160:163], v[184:187], v[56:59]
	v_mfma_f32_16x16x32_bf16 v[44:47], v[144:147], v[192:195], v[44:47]
	v_mfma_f32_16x16x32_bf16 v[40:43], v[160:163], v[192:195], v[40:43]
	v_mfma_f32_16x16x32_bf16 v[28:31], v[144:147], v[200:203], v[28:31]
	v_mfma_f32_16x16x32_bf16 v[24:27], v[160:163], v[200:203], v[24:27]
	v_mfma_f32_16x16x32_bf16 v[12:15], v[144:147], v[208:211], v[12:15]
	v_mfma_f32_16x16x32_bf16 v[8:11], v[160:163], v[208:211], v[8:11]
	v_mfma_f32_16x16x32_bf16 v[60:63], v[156:159], v[188:191], v[60:63]
	v_mfma_f32_16x16x32_bf16 v[56:59], v[164:167], v[188:191], v[56:59]
	v_mfma_f32_16x16x32_bf16 v[44:47], v[156:159], v[196:199], v[44:47]
	v_mfma_f32_16x16x32_bf16 v[40:43], v[164:167], v[196:199], v[40:43]
	v_mfma_f32_16x16x32_bf16 v[28:31], v[156:159], v[204:207], v[28:31]
	v_mfma_f32_16x16x32_bf16 v[24:27], v[164:167], v[204:207], v[24:27]
	v_mfma_f32_16x16x32_bf16 v[12:15], v[156:159], v[212:215], v[12:15]
	v_mfma_f32_16x16x32_bf16 v[8:11], v[164:167], v[212:215], v[8:11]
	v_mfma_f32_16x16x32_bf16 v[52:55], v[168:171], v[184:187], v[52:55]
	v_mfma_f32_16x16x32_bf16 v[48:51], v[176:179], v[184:187], v[48:51]
	v_mfma_f32_16x16x32_bf16 v[36:39], v[168:171], v[192:195], v[36:39]
	v_mfma_f32_16x16x32_bf16 v[32:35], v[176:179], v[192:195], v[32:35]
	v_mfma_f32_16x16x32_bf16 v[20:23], v[168:171], v[200:203], v[20:23]
	v_mfma_f32_16x16x32_bf16 v[16:19], v[176:179], v[200:203], v[16:19]
	v_mfma_f32_16x16x32_bf16 v[4:7], v[168:171], v[208:211], v[4:7]
	v_mfma_f32_16x16x32_bf16 v[0:3], v[176:179], v[208:211], v[0:3]
	v_mfma_f32_16x16x32_bf16 v[52:55], v[172:175], v[188:191], v[52:55]
	v_mfma_f32_16x16x32_bf16 v[48:51], v[180:183], v[188:191], v[48:51]
	v_mfma_f32_16x16x32_bf16 v[36:39], v[172:175], v[196:199], v[36:39]
	v_mfma_f32_16x16x32_bf16 v[32:35], v[180:183], v[196:199], v[32:35]
	v_mfma_f32_16x16x32_bf16 v[20:23], v[172:175], v[204:207], v[20:23]
	v_mfma_f32_16x16x32_bf16 v[16:19], v[180:183], v[204:207], v[16:19]
	v_mfma_f32_16x16x32_bf16 v[4:7], v[172:175], v[212:215], v[4:7]
	v_mfma_f32_16x16x32_bf16 v[0:3], v[180:183], v[212:215], v[0:3]
	s_barrier
	s_add_i32 s54, 0, 0x18000
	s_add_i32 s55, 0, 0x1c000
	v_add_u32_e32 v164, s54, v151
	v_add_u32_e32 v180, s55, v151
	ds_read_b128 v[144:147], v164
	ds_read_b128 v[156:159], v164 offset:1024
	ds_read_b128 v[160:163], v164 offset:2048
	ds_read_b128 v[164:167], v164 offset:3072
	ds_read_b128 v[168:171], v180
	ds_read_b128 v[172:175], v180 offset:1024
	ds_read_b128 v[176:179], v180 offset:2048
	ds_read_b128 v[180:183], v180 offset:3072
	s_add_u32 s26, s36, 0x300000
	s_addc_u32 s27, s37, 0
	s_mov_b32 m0, s41
	ds_read_b128 v[184:187], v155 offset:32768
	ds_read_b128 v[188:191], v155 offset:33792
	ds_read_b128 v[192:195], v155 offset:34816
	ds_read_b128 v[196:199], v155 offset:35840
	ds_read_b128 v[200:203], v155 offset:36864
	ds_read_b128 v[204:207], v155 offset:37888
	ds_read_b128 v[208:211], v155 offset:38912
	ds_read_b128 v[212:215], v155 offset:39936
	global_load_lds_dwordx4 v128, s[26:27]
	s_mov_b32 m0, s42
	s_nop 0
	global_load_lds_dwordx4 v132, s[26:27]
	s_waitcnt vmcnt(8)
	s_waitcnt lgkmcnt(0)
	s_barrier
	s_waitcnt lgkmcnt(0)
	v_mfma_f32_16x16x32_bf16 v[124:127], v[144:147], v[184:187], v[124:127]
	v_mfma_f32_16x16x32_bf16 v[120:123], v[160:163], v[184:187], v[120:123]
	v_mfma_f32_16x16x32_bf16 v[108:111], v[144:147], v[192:195], v[108:111]
	v_mfma_f32_16x16x32_bf16 v[104:107], v[160:163], v[192:195], v[104:107]
	v_mfma_f32_16x16x32_bf16 v[92:95], v[144:147], v[200:203], v[92:95]
	v_mfma_f32_16x16x32_bf16 v[88:91], v[160:163], v[200:203], v[88:91]
	v_mfma_f32_16x16x32_bf16 v[76:79], v[144:147], v[208:211], v[76:79]
	v_mfma_f32_16x16x32_bf16 v[72:75], v[160:163], v[208:211], v[72:75]
	v_mfma_f32_16x16x32_bf16 v[124:127], v[156:159], v[188:191], v[124:127]
	v_mfma_f32_16x16x32_bf16 v[120:123], v[164:167], v[188:191], v[120:123]
	v_mfma_f32_16x16x32_bf16 v[108:111], v[156:159], v[196:199], v[108:111]
	v_mfma_f32_16x16x32_bf16 v[104:107], v[164:167], v[196:199], v[104:107]
	v_mfma_f32_16x16x32_bf16 v[92:95], v[156:159], v[204:207], v[92:95]
	v_mfma_f32_16x16x32_bf16 v[88:91], v[164:167], v[204:207], v[88:91]
	v_mfma_f32_16x16x32_bf16 v[76:79], v[156:159], v[212:215], v[76:79]
	v_mfma_f32_16x16x32_bf16 v[72:75], v[164:167], v[212:215], v[72:75]
	v_mfma_f32_16x16x32_bf16 v[116:119], v[168:171], v[184:187], v[116:119]
	v_mfma_f32_16x16x32_bf16 v[112:115], v[176:179], v[184:187], v[112:115]
	v_mfma_f32_16x16x32_bf16 v[100:103], v[168:171], v[192:195], v[100:103]
	v_mfma_f32_16x16x32_bf16 v[96:99], v[176:179], v[192:195], v[96:99]
	v_mfma_f32_16x16x32_bf16 v[84:87], v[168:171], v[200:203], v[84:87]
	v_mfma_f32_16x16x32_bf16 v[80:83], v[176:179], v[200:203], v[80:83]
	v_mfma_f32_16x16x32_bf16 v[68:71], v[168:171], v[208:211], v[68:71]
	v_mfma_f32_16x16x32_bf16 v[64:67], v[176:179], v[208:211], v[64:67]
	v_mfma_f32_16x16x32_bf16 v[116:119], v[172:175], v[188:191], v[116:119]
	v_mfma_f32_16x16x32_bf16 v[112:115], v[180:183], v[188:191], v[112:115]
	v_mfma_f32_16x16x32_bf16 v[100:103], v[172:175], v[196:199], v[100:103]
	v_mfma_f32_16x16x32_bf16 v[96:99], v[180:183], v[196:199], v[96:99]
	v_mfma_f32_16x16x32_bf16 v[84:87], v[172:175], v[204:207], v[84:87]
	v_mfma_f32_16x16x32_bf16 v[80:83], v[180:183], v[204:207], v[80:83]
	v_mfma_f32_16x16x32_bf16 v[68:71], v[172:175], v[212:215], v[68:71]
	v_mfma_f32_16x16x32_bf16 v[64:67], v[180:183], v[212:215], v[64:67]
	s_barrier
	s_add_i32 s26, s54, s38
	s_mov_b32 m0, s26
	ds_read_b128 v[184:187], v155 offset:49152
	ds_read_b128 v[188:191], v155 offset:50176
	ds_read_b128 v[192:195], v155 offset:51200
	ds_read_b128 v[196:199], v155 offset:52224
	ds_read_b128 v[200:203], v155 offset:53248
	ds_read_b128 v[204:207], v155 offset:54272
	ds_read_b128 v[208:211], v155 offset:55296
	ds_read_b128 v[212:215], v155 offset:56320
	s_add_u32 s100, s30, 0x80
	s_addc_u32 s101, s31, 0
	global_load_lds_dwordx4 v130, s[100:101]
	s_add_i32 m0, s26, 0x2000
	s_add_u32 s26, s30, 0x300080
	v_lshl_add_u64 v[148:149], v[216:217], 0, s[10:11]
	s_addc_u32 s27, s31, 0
	s_add_i32 s30, s55, s38
	global_load_lds_dwordx4 v[148:149], off
	s_mov_b32 m0, s30
	s_nop 0
	global_load_lds_dwordx4 v130, s[26:27]
	s_add_i32 m0, s30, 0x2000
	s_nop 0
	global_load_lds_dwordx4 v134, s[26:27]
	s_mov_b32 m0, s44
	s_nop 0
	s_add_u32 s100, s36, 0x80
	s_addc_u32 s101, s37, 0
	global_load_lds_dwordx4 v128, s[100:101]
	s_mov_b32 m0, s45
	s_nop 0
	s_add_u32 s100, s36, 0x80
	s_addc_u32 s101, s37, 0
	global_load_lds_dwordx4 v132, s[100:101]
	s_waitcnt vmcnt(8)
	s_waitcnt lgkmcnt(0)
	s_barrier
	s_waitcnt lgkmcnt(0)
	v_mfma_f32_16x16x32_bf16 v[60:63], v[144:147], v[184:187], v[60:63]
	v_mfma_f32_16x16x32_bf16 v[56:59], v[160:163], v[184:187], v[56:59]
	v_mfma_f32_16x16x32_bf16 v[44:47], v[144:147], v[192:195], v[44:47]
	v_mfma_f32_16x16x32_bf16 v[40:43], v[160:163], v[192:195], v[40:43]
	v_mfma_f32_16x16x32_bf16 v[28:31], v[144:147], v[200:203], v[28:31]
	v_mfma_f32_16x16x32_bf16 v[24:27], v[160:163], v[200:203], v[24:27]
	v_mfma_f32_16x16x32_bf16 v[12:15], v[144:147], v[208:211], v[12:15]
	v_mfma_f32_16x16x32_bf16 v[8:11], v[160:163], v[208:211], v[8:11]
	v_mfma_f32_16x16x32_bf16 v[60:63], v[156:159], v[188:191], v[60:63]
	v_mfma_f32_16x16x32_bf16 v[56:59], v[164:167], v[188:191], v[56:59]
	v_mfma_f32_16x16x32_bf16 v[44:47], v[156:159], v[196:199], v[44:47]
	v_mfma_f32_16x16x32_bf16 v[40:43], v[164:167], v[196:199], v[40:43]
	v_mfma_f32_16x16x32_bf16 v[28:31], v[156:159], v[204:207], v[28:31]
	v_mfma_f32_16x16x32_bf16 v[24:27], v[164:167], v[204:207], v[24:27]
	v_mfma_f32_16x16x32_bf16 v[12:15], v[156:159], v[212:215], v[12:15]
	v_mfma_f32_16x16x32_bf16 v[8:11], v[164:167], v[212:215], v[8:11]
	v_mfma_f32_16x16x32_bf16 v[52:55], v[168:171], v[184:187], v[52:55]
	v_mfma_f32_16x16x32_bf16 v[48:51], v[176:179], v[184:187], v[48:51]
	v_mfma_f32_16x16x32_bf16 v[36:39], v[168:171], v[192:195], v[36:39]
	v_mfma_f32_16x16x32_bf16 v[32:35], v[176:179], v[192:195], v[32:35]
	v_mfma_f32_16x16x32_bf16 v[20:23], v[168:171], v[200:203], v[20:23]
	v_mfma_f32_16x16x32_bf16 v[16:19], v[176:179], v[200:203], v[16:19]
	v_mfma_f32_16x16x32_bf16 v[4:7], v[168:171], v[208:211], v[4:7]
	v_mfma_f32_16x16x32_bf16 v[0:3], v[176:179], v[208:211], v[0:3]
	v_mfma_f32_16x16x32_bf16 v[52:55], v[172:175], v[188:191], v[52:55]
	v_mfma_f32_16x16x32_bf16 v[48:51], v[180:183], v[188:191], v[48:51]
	v_mfma_f32_16x16x32_bf16 v[36:39], v[172:175], v[196:199], v[36:39]
	v_mfma_f32_16x16x32_bf16 v[32:35], v[180:183], v[196:199], v[32:35]
	v_mfma_f32_16x16x32_bf16 v[20:23], v[172:175], v[204:207], v[20:23]
	v_mfma_f32_16x16x32_bf16 v[16:19], v[180:183], v[204:207], v[16:19]
	v_mfma_f32_16x16x32_bf16 v[4:7], v[172:175], v[212:215], v[4:7]
	v_mfma_f32_16x16x32_bf16 v[0:3], v[180:183], v[212:215], v[0:3]
	s_barrier
	s_add_i32 s53, s53, 2
	s_add_u32 s34, s34, 0x100
	s_addc_u32 s35, s35, 0
	s_cmpk_gt_u32 s53, 0xbd
	s_mov_b64 s[26:27], s[28:29]
	s_cbranch_scc0 .LBB0_1077
	s_setprio 0
	s_and_b64 vcc, exec, s[12:13]
	s_cbranch_vccz .LBB0_1080
	s_barrier

.Lmy_prio_skip7:
.LBB0_1313:
	ds_read_b128 v[48:51], v163
	ds_read_b128 v[52:55], v163 offset:1024
	ds_read_b128 v[152:155], v163 offset:2048
	ds_read_b128 v[156:159], v163 offset:3072
	ds_read_b128 v[168:171], v164
	ds_read_b128 v[172:175], v164 offset:1024
	ds_read_b128 v[176:179], v164 offset:2048
	ds_read_b128 v[180:183], v164 offset:3072
	s_add_u32 s42, s40, 0xfff00080
	s_addc_u32 s43, s41, -1
	s_cmp_eq_u32 s60, 60
	s_cselect_b32 s45, s14, s43
	s_cselect_b32 s44, s29, s42
	s_cselect_b32 s43, s27, s35
	s_cselect_b32 s42, s39, s34
	s_add_i32 m0, s47, 0xc000
	ds_read_b128 v[184:187], v165
	ds_read_b128 v[188:191], v165 offset:1024
	ds_read_b128 v[192:195], v165 offset:2048
	ds_read_b128 v[196:199], v165 offset:3072
	ds_read_b128 v[200:203], v165 offset:4096
	ds_read_b128 v[204:207], v165 offset:5120
	ds_read_b128 v[208:211], v165 offset:6144
	ds_read_b128 v[212:215], v165 offset:7168
	global_load_lds_dwordx4 v144, s[40:41]
	s_add_i32 m0, s47, 0xe000
	s_nop 0
	global_load_lds_dwordx4 v146, s[40:41]
	s_waitcnt vmcnt(8)
	s_waitcnt lgkmcnt(0)
	s_barrier
	s_waitcnt lgkmcnt(0)
	v_mfma_f32_16x16x32_bf16 v[44:47], v[48:51], v[184:187], v[44:47]
	v_mfma_f32_16x16x32_bf16 v[40:43], v[152:155], v[184:187], v[40:43]
	v_mfma_f32_16x16x32_bf16 v[124:127], v[48:51], v[192:195], v[124:127]
	v_mfma_f32_16x16x32_bf16 v[120:123], v[152:155], v[192:195], v[120:123]
	v_mfma_f32_16x16x32_bf16 v[108:111], v[48:51], v[200:203], v[108:111]
	v_mfma_f32_16x16x32_bf16 v[104:107], v[152:155], v[200:203], v[104:107]
	v_mfma_f32_16x16x32_bf16 v[92:95], v[48:51], v[208:211], v[92:95]
	v_mfma_f32_16x16x32_bf16 v[88:91], v[152:155], v[208:211], v[88:91]
	v_mfma_f32_16x16x32_bf16 v[44:47], v[52:55], v[188:191], v[44:47]
	v_mfma_f32_16x16x32_bf16 v[40:43], v[156:159], v[188:191], v[40:43]
	v_mfma_f32_16x16x32_bf16 v[124:127], v[52:55], v[196:199], v[124:127]
	v_mfma_f32_16x16x32_bf16 v[120:123], v[156:159], v[196:199], v[120:123]
	v_mfma_f32_16x16x32_bf16 v[108:111], v[52:55], v[204:207], v[108:111]
	v_mfma_f32_16x16x32_bf16 v[104:107], v[156:159], v[204:207], v[104:107]
	v_mfma_f32_16x16x32_bf16 v[92:95], v[52:55], v[212:215], v[92:95]
	v_mfma_f32_16x16x32_bf16 v[88:91], v[156:159], v[212:215], v[88:91]
	v_mfma_f32_16x16x32_bf16 v[132:135], v[168:171], v[184:187], v[132:135]
	v_mfma_f32_16x16x32_bf16 v[128:131], v[176:179], v[184:187], v[128:131]
	v_mfma_f32_16x16x32_bf16 v[116:119], v[168:171], v[192:195], v[116:119]
	v_mfma_f32_16x16x32_bf16 v[112:115], v[176:179], v[192:195], v[112:115]
	v_mfma_f32_16x16x32_bf16 v[100:103], v[168:171], v[200:203], v[100:103]
	v_mfma_f32_16x16x32_bf16 v[96:99], v[176:179], v[200:203], v[96:99]
	v_mfma_f32_16x16x32_bf16 v[84:87], v[168:171], v[208:211], v[84:87]
	v_mfma_f32_16x16x32_bf16 v[80:83], v[176:179], v[208:211], v[80:83]
	v_mfma_f32_16x16x32_bf16 v[132:135], v[172:175], v[188:191], v[132:135]
	v_mfma_f32_16x16x32_bf16 v[128:131], v[180:183], v[188:191], v[128:131]
	v_mfma_f32_16x16x32_bf16 v[116:119], v[172:175], v[196:199], v[116:119]
	v_mfma_f32_16x16x32_bf16 v[112:115], v[180:183], v[196:199], v[112:115]
	v_mfma_f32_16x16x32_bf16 v[100:103], v[172:175], v[204:207], v[100:103]
	v_mfma_f32_16x16x32_bf16 v[96:99], v[180:183], v[204:207], v[96:99]
	v_mfma_f32_16x16x32_bf16 v[84:87], v[172:175], v[212:215], v[84:87]
	v_mfma_f32_16x16x32_bf16 v[80:83], v[180:183], v[212:215], v[80:83]
	s_barrier
	s_add_i32 s61, s56, s46
	s_mov_b32 m0, s61
	ds_read_b128 v[184:187], v165 offset:16384
	ds_read_b128 v[188:191], v165 offset:17408
	ds_read_b128 v[192:195], v165 offset:18432
	ds_read_b128 v[196:199], v165 offset:19456
	ds_read_b128 v[200:203], v165 offset:20480
	ds_read_b128 v[204:207], v165 offset:21504
	ds_read_b128 v[208:211], v165 offset:22528
	ds_read_b128 v[212:215], v165 offset:23552
	global_load_lds_dwordx4 v138, s[42:43]
	s_add_i32 m0, s61, 0x2000
	s_add_u32 s62, s42, 0x100000
	v_lshl_add_u64 v[218:219], s[42:43], 0, v[142:143]
	s_addc_u32 s63, s43, 0
	s_add_i32 s61, s57, s46
	global_load_lds_dwordx4 v142, s[42:43]
	s_mov_b32 m0, s61
	v_lshl_add_u64 v[222:223], s[44:45], 0, v[140:141]
	global_load_lds_dwordx4 v138, s[62:63]
	s_add_i32 m0, s61, 0x2000
	s_nop 0
	global_load_lds_dwordx4 v142, s[62:63]
	v_lshl_add_u64 v[220:221], s[44:45], 0, v[136:137]
	s_mov_b32 m0, s47
	s_nop 0
	global_load_lds_dwordx4 v136, s[44:45]
	s_mov_b32 m0, s48
	s_nop 0
	global_load_lds_dwordx4 v140, s[44:45]
	s_waitcnt vmcnt(8)
	s_waitcnt lgkmcnt(0)
	s_barrier
	s_waitcnt lgkmcnt(0)
	v_mfma_f32_16x16x32_bf16 v[76:79], v[48:51], v[184:187], v[76:79]
	v_mfma_f32_16x16x32_bf16 v[72:75], v[152:155], v[184:187], v[72:75]
	v_mfma_f32_16x16x32_bf16 v[60:63], v[48:51], v[192:195], v[60:63]
	v_mfma_f32_16x16x32_bf16 v[56:59], v[152:155], v[192:195], v[56:59]
	v_mfma_f32_16x16x32_bf16 v[28:31], v[48:51], v[200:203], v[28:31]
	v_mfma_f32_16x16x32_bf16 v[24:27], v[152:155], v[200:203], v[24:27]
	v_mfma_f32_16x16x32_bf16 v[12:15], v[48:51], v[208:211], v[12:15]
	v_mfma_f32_16x16x32_bf16 v[8:11], v[152:155], v[208:211], v[8:11]
	v_mfma_f32_16x16x32_bf16 v[76:79], v[52:55], v[188:191], v[76:79]
	v_mfma_f32_16x16x32_bf16 v[72:75], v[156:159], v[188:191], v[72:75]
	v_mfma_f32_16x16x32_bf16 v[60:63], v[52:55], v[196:199], v[60:63]
	v_mfma_f32_16x16x32_bf16 v[56:59], v[156:159], v[196:199], v[56:59]
	v_mfma_f32_16x16x32_bf16 v[28:31], v[52:55], v[204:207], v[28:31]
	v_mfma_f32_16x16x32_bf16 v[24:27], v[156:159], v[204:207], v[24:27]
	v_mfma_f32_16x16x32_bf16 v[12:15], v[52:55], v[212:215], v[12:15]
	v_mfma_f32_16x16x32_bf16 v[8:11], v[156:159], v[212:215], v[8:11]
	v_mfma_f32_16x16x32_bf16 v[36:39], v[168:171], v[192:195], v[36:39]
	v_mfma_f32_16x16x32_bf16 v[32:35], v[176:179], v[192:195], v[32:35]
	v_mfma_f32_16x16x32_bf16 v[20:23], v[168:171], v[200:203], v[20:23]
	v_mfma_f32_16x16x32_bf16 v[16:19], v[176:179], v[200:203], v[16:19]
	v_mfma_f32_16x16x32_bf16 v[4:7], v[168:171], v[208:211], v[4:7]
	v_mfma_f32_16x16x32_bf16 v[0:3], v[176:179], v[208:211], v[0:3]
	v_mfma_f32_16x16x32_bf16 v[48:51], v[168:171], v[184:187], v[68:71]
	v_mfma_f32_16x16x32_bf16 v[52:55], v[176:179], v[184:187], v[64:67]
	v_mfma_f32_16x16x32_bf16 v[36:39], v[172:175], v[196:199], v[36:39]
	v_mfma_f32_16x16x32_bf16 v[32:35], v[180:183], v[196:199], v[32:35]
	v_mfma_f32_16x16x32_bf16 v[20:23], v[172:175], v[204:207], v[20:23]
	v_mfma_f32_16x16x32_bf16 v[16:19], v[180:183], v[204:207], v[16:19]
	v_mfma_f32_16x16x32_bf16 v[4:7], v[172:175], v[212:215], v[4:7]
	v_mfma_f32_16x16x32_bf16 v[0:3], v[180:183], v[212:215], v[0:3]
	v_mfma_f32_16x16x32_bf16 v[48:51], v[172:175], v[188:191], v[48:51]
	v_mfma_f32_16x16x32_bf16 v[52:55], v[180:183], v[188:191], v[52:55]
	s_barrier
	s_add_i32 s61, 0, 0x18000
	s_add_i32 s62, 0, 0x1c000
	v_add_u32_e32 v156, s61, v161
	v_add_u32_e32 v167, s62, v161
	ds_read_b128 v[64:67], v156
	ds_read_b128 v[68:71], v156 offset:1024
	ds_read_b128 v[152:155], v156 offset:2048
	ds_read_b128 v[156:159], v156 offset:3072
	ds_read_b128 v[168:171], v167
	ds_read_b128 v[172:175], v167 offset:1024
	ds_read_b128 v[176:179], v167 offset:2048
	ds_read_b128 v[180:183], v167 offset:3072
	s_add_u32 s44, s44, 0x100000
	s_addc_u32 s45, s45, 0
	s_mov_b32 m0, s49
	ds_read_b128 v[184:187], v165 offset:32768
	ds_read_b128 v[188:191], v165 offset:33792
	ds_read_b128 v[192:195], v165 offset:34816
	ds_read_b128 v[196:199], v165 offset:35840
	ds_read_b128 v[200:203], v165 offset:36864
	ds_read_b128 v[204:207], v165 offset:37888
	ds_read_b128 v[208:211], v165 offset:38912
	ds_read_b128 v[212:215], v165 offset:39936
	global_load_lds_dwordx4 v136, s[44:45]
	s_mov_b32 m0, s50
	s_nop 0
	global_load_lds_dwordx4 v140, s[44:45]
	s_waitcnt vmcnt(8)
	s_waitcnt lgkmcnt(0)
	s_barrier
	s_waitcnt lgkmcnt(0)
	v_mfma_f32_16x16x32_bf16 v[44:47], v[64:67], v[184:187], v[44:47]
	v_mfma_f32_16x16x32_bf16 v[40:43], v[152:155], v[184:187], v[40:43]
	v_mfma_f32_16x16x32_bf16 v[124:127], v[64:67], v[192:195], v[124:127]
	v_mfma_f32_16x16x32_bf16 v[120:123], v[152:155], v[192:195], v[120:123]
	v_mfma_f32_16x16x32_bf16 v[108:111], v[64:67], v[200:203], v[108:111]
	v_mfma_f32_16x16x32_bf16 v[104:107], v[152:155], v[200:203], v[104:107]
	v_mfma_f32_16x16x32_bf16 v[92:95], v[64:67], v[208:211], v[92:95]
	v_mfma_f32_16x16x32_bf16 v[88:91], v[152:155], v[208:211], v[88:91]
	v_mfma_f32_16x16x32_bf16 v[44:47], v[68:71], v[188:191], v[44:47]
	v_mfma_f32_16x16x32_bf16 v[40:43], v[156:159], v[188:191], v[40:43]
	v_mfma_f32_16x16x32_bf16 v[124:127], v[68:71], v[196:199], v[124:127]
	v_mfma_f32_16x16x32_bf16 v[120:123], v[156:159], v[196:199], v[120:123]
	v_mfma_f32_16x16x32_bf16 v[108:111], v[68:71], v[204:207], v[108:111]
	v_mfma_f32_16x16x32_bf16 v[104:107], v[156:159], v[204:207], v[104:107]
	v_mfma_f32_16x16x32_bf16 v[92:95], v[68:71], v[212:215], v[92:95]
	v_mfma_f32_16x16x32_bf16 v[88:91], v[156:159], v[212:215], v[88:91]
	v_mfma_f32_16x16x32_bf16 v[132:135], v[168:171], v[184:187], v[132:135]
	v_mfma_f32_16x16x32_bf16 v[128:131], v[176:179], v[184:187], v[128:131]
	v_mfma_f32_16x16x32_bf16 v[116:119], v[168:171], v[192:195], v[116:119]
	v_mfma_f32_16x16x32_bf16 v[112:115], v[176:179], v[192:195], v[112:115]
	v_mfma_f32_16x16x32_bf16 v[100:103], v[168:171], v[200:203], v[100:103]
	v_mfma_f32_16x16x32_bf16 v[96:99], v[176:179], v[200:203], v[96:99]
	v_mfma_f32_16x16x32_bf16 v[84:87], v[168:171], v[208:211], v[84:87]
	v_mfma_f32_16x16x32_bf16 v[80:83], v[176:179], v[208:211], v[80:83]
	v_mfma_f32_16x16x32_bf16 v[132:135], v[172:175], v[188:191], v[132:135]
	v_mfma_f32_16x16x32_bf16 v[128:131], v[180:183], v[188:191], v[128:131]
	v_mfma_f32_16x16x32_bf16 v[116:119], v[172:175], v[196:199], v[116:119]
	v_mfma_f32_16x16x32_bf16 v[112:115], v[180:183], v[196:199], v[112:115]
	v_mfma_f32_16x16x32_bf16 v[100:103], v[172:175], v[204:207], v[100:103]
	v_mfma_f32_16x16x32_bf16 v[96:99], v[180:183], v[204:207], v[96:99]
	v_mfma_f32_16x16x32_bf16 v[84:87], v[172:175], v[212:215], v[84:87]
	v_mfma_f32_16x16x32_bf16 v[80:83], v[180:183], v[212:215], v[80:83]
	s_barrier
	s_add_i32 s44, s61, s46
	s_mov_b32 m0, s44
	ds_read_b128 v[184:187], v165 offset:49152
	ds_read_b128 v[188:191], v165 offset:50176
	ds_read_b128 v[192:195], v165 offset:51200
	ds_read_b128 v[196:199], v165 offset:52224
	ds_read_b128 v[200:203], v165 offset:53248
	ds_read_b128 v[204:207], v165 offset:54272
	ds_read_b128 v[208:211], v165 offset:55296
	ds_read_b128 v[212:215], v165 offset:56320
	s_add_u32 s100, s42, 0x80
	s_addc_u32 s101, s43, 0
	global_load_lds_dwordx4 v138, s[100:101]
	s_add_i32 m0, s44, 0x2000
	s_add_u32 s42, s42, 0x100080
	v_lshl_add_u64 v[216:217], v[218:219], 0, s[22:23]
	s_addc_u32 s43, s43, 0
	s_add_i32 s44, s62, s46
	global_load_lds_dwordx4 v[216:217], off
	s_mov_b32 m0, s44
	s_nop 0
	global_load_lds_dwordx4 v138, s[42:43]
	s_add_i32 m0, s44, 0x2000
	s_nop 0
	global_load_lds_dwordx4 v142, s[42:43]
	v_lshl_add_u64 v[216:217], v[220:221], 0, s[22:23]
	s_mov_b32 m0, s52
	s_nop 0
	global_load_lds_dwordx4 v[216:217], off
	v_lshl_add_u64 v[216:217], v[222:223], 0, s[22:23]
	s_mov_b32 m0, s53
	s_nop 0
	global_load_lds_dwordx4 v[216:217], off
	s_waitcnt vmcnt(8)
	s_waitcnt lgkmcnt(0)
	s_barrier
	s_waitcnt lgkmcnt(0)
	v_mfma_f32_16x16x32_bf16 v[76:79], v[64:67], v[184:187], v[76:79]
	v_mfma_f32_16x16x32_bf16 v[72:75], v[152:155], v[184:187], v[72:75]
	v_mfma_f32_16x16x32_bf16 v[60:63], v[64:67], v[192:195], v[60:63]
	v_mfma_f32_16x16x32_bf16 v[56:59], v[152:155], v[192:195], v[56:59]
	v_mfma_f32_16x16x32_bf16 v[28:31], v[64:67], v[200:203], v[28:31]
	v_mfma_f32_16x16x32_bf16 v[24:27], v[152:155], v[200:203], v[24:27]
	v_mfma_f32_16x16x32_bf16 v[12:15], v[64:67], v[208:211], v[12:15]
	v_mfma_f32_16x16x32_bf16 v[8:11], v[152:155], v[208:211], v[8:11]
	v_mfma_f32_16x16x32_bf16 v[76:79], v[68:71], v[188:191], v[76:79]
	v_mfma_f32_16x16x32_bf16 v[72:75], v[156:159], v[188:191], v[72:75]
	v_mfma_f32_16x16x32_bf16 v[60:63], v[68:71], v[196:199], v[60:63]
	v_mfma_f32_16x16x32_bf16 v[56:59], v[156:159], v[196:199], v[56:59]
	v_mfma_f32_16x16x32_bf16 v[28:31], v[68:71], v[204:207], v[28:31]
	v_mfma_f32_16x16x32_bf16 v[24:27], v[156:159], v[204:207], v[24:27]
	v_mfma_f32_16x16x32_bf16 v[12:15], v[68:71], v[212:215], v[12:15]
	v_mfma_f32_16x16x32_bf16 v[8:11], v[156:159], v[212:215], v[8:11]
	v_mfma_f32_16x16x32_bf16 v[48:51], v[168:171], v[184:187], v[48:51]
	v_mfma_f32_16x16x32_bf16 v[68:71], v[172:175], v[188:191], v[48:51]
	v_mfma_f32_16x16x32_bf16 v[48:51], v[176:179], v[184:187], v[52:55]
	v_mfma_f32_16x16x32_bf16 v[36:39], v[168:171], v[192:195], v[36:39]
	v_mfma_f32_16x16x32_bf16 v[32:35], v[176:179], v[192:195], v[32:35]
	v_mfma_f32_16x16x32_bf16 v[20:23], v[168:171], v[200:203], v[20:23]
	v_mfma_f32_16x16x32_bf16 v[16:19], v[176:179], v[200:203], v[16:19]
	v_mfma_f32_16x16x32_bf16 v[4:7], v[168:171], v[208:211], v[4:7]
	v_mfma_f32_16x16x32_bf16 v[0:3], v[176:179], v[208:211], v[0:3]
	v_mfma_f32_16x16x32_bf16 v[64:67], v[180:183], v[188:191], v[48:51]
	v_mfma_f32_16x16x32_bf16 v[36:39], v[172:175], v[196:199], v[36:39]
	v_mfma_f32_16x16x32_bf16 v[32:35], v[180:183], v[196:199], v[32:35]
	v_mfma_f32_16x16x32_bf16 v[20:23], v[172:175], v[204:207], v[20:23]
	v_mfma_f32_16x16x32_bf16 v[16:19], v[180:183], v[204:207], v[16:19]
	v_mfma_f32_16x16x32_bf16 v[4:7], v[172:175], v[212:215], v[4:7]
	v_mfma_f32_16x16x32_bf16 v[0:3], v[180:183], v[212:215], v[0:3]
	s_barrier
	s_add_i32 s60, s60, 2
	s_add_u32 s40, s40, 0x100
	s_addc_u32 s41, s41, 0
	s_add_u32 s34, s34, 0x100
	s_addc_u32 s35, s35, 0
	s_cmp_gt_u32 s60, 61
	s_cbranch_scc0 .LBB0_1313
	s_setprio 0
	s_and_b64 vcc, exec, s[24:25]
	s_cbranch_vccz .LBB0_1316
	s_barrier
